# lane-permuted bf16 row stores also in the three hand-written EpiResid epilogues
# baseline (speedup 1.0000x reference)
.LBB0_1016:
	v_mbcnt_lo_u32_b32 v252, -1, 0
	v_mbcnt_hi_u32_b32 v252, -1, v252
	v_and_b32_e32 v250, 3, v252
	v_lshrrev_b32_e32 v252, 2, v252
	v_lshl_or_b32 v252, v250, 4, v252
	v_lshlrev_b32_e32 v252, 2, v252
	v_lshl_add_u32 v238, s44, 8, v146
	v_and_b32_e32 v240, 0xe0, v148
	v_and_b32_e32 v241, 4, v148
	v_lshl_or_b32 v240, v241, 2, v240
	v_and_b32_e32 v241, 8, v148
	v_or_b32_e32 v240, v240, v241
	v_lshl_or_b32 v240, s45, 8, v240
	v_mov_b32_e32 v241, 0
	v_ashrrev_i32_e32 v239, 31, v238
	v_readlane_b32 s20, v234, 22
	v_readlane_b32 s21, v234, 23
	v_lshlrev_b64 v[244:245], 11, v[238:239]
	v_lshl_add_u64 v[244:245], v[244:245], 0, v[240:241]
	v_lshl_add_u64 v[144:145], v[244:245], 1, s[20:21]
	s_mov_b32 s101, 0
	global_load_dwordx4 v[140:143], v[144:145], off
	global_load_dwordx4 v[154:157], v[144:145], off offset:256
	s_mov_b32 s100, 0x10000
	v_lshl_add_u64 v[236:237], v[144:145], 0, s[100:101]
	global_load_dwordx4 v[158:161], v[236:237], off
	global_load_dwordx4 v[162:165], v[236:237], off offset:256
	s_mov_b32 s100, 0x20000
	v_lshl_add_u64 v[236:237], v[144:145], 0, s[100:101]
	global_load_dwordx4 v[166:169], v[236:237], off
	global_load_dwordx4 v[170:173], v[236:237], off offset:256
	s_mov_b32 s100, 0x30000
	v_lshl_add_u64 v[236:237], v[144:145], 0, s[100:101]
	global_load_dwordx4 v[174:177], v[236:237], off
	global_load_dwordx4 v[178:181], v[236:237], off offset:256
	s_mov_b32 s100, 0x80000
	v_lshl_add_u64 v[236:237], v[144:145], 0, s[100:101]
	global_load_dwordx4 v[184:187], v[236:237], off
	global_load_dwordx4 v[190:193], v[236:237], off offset:256
	s_mov_b32 s100, 0x90000
	v_lshl_add_u64 v[236:237], v[144:145], 0, s[100:101]
	global_load_dwordx4 v[194:197], v[236:237], off
	global_load_dwordx4 v[198:201], v[236:237], off offset:256
	s_mov_b32 s100, 0xa0000
	v_lshl_add_u64 v[236:237], v[144:145], 0, s[100:101]
	global_load_dwordx4 v[202:205], v[236:237], off
	global_load_dwordx4 v[206:209], v[236:237], off offset:256
	s_mov_b32 s100, 0xb0000
	v_lshl_add_u64 v[236:237], v[144:145], 0, s[100:101]
	global_load_dwordx4 v[210:213], v[236:237], off
	global_load_dwordx4 v[214:217], v[236:237], off offset:256
	v_xor_b32_e32 v153, 16, v152
	v_xor_b32_e32 v242, 32, v152
	v_lshlrev_b32_e32 v153, 2, v153
	v_lshlrev_b32_e32 v242, 2, v242
	v_permlane16_swap_b32_e32 v124, v120
	v_permlane16_swap_b32_e32 v125, v121
	v_permlane16_swap_b32_e32 v126, v122
	v_permlane16_swap_b32_e32 v127, v123
	v_permlane16_swap_b32_e32 v116, v112
	v_permlane16_swap_b32_e32 v117, v113
	v_permlane16_swap_b32_e32 v118, v114
	v_permlane16_swap_b32_e32 v119, v115
	v_permlane16_swap_b32_e32 v108, v104
	v_permlane16_swap_b32_e32 v109, v105
	v_permlane16_swap_b32_e32 v110, v106
	v_permlane16_swap_b32_e32 v111, v107
	v_permlane16_swap_b32_e32 v100, v96
	v_permlane16_swap_b32_e32 v101, v97
	v_permlane16_swap_b32_e32 v102, v98
	v_permlane16_swap_b32_e32 v103, v99
	v_permlane16_swap_b32_e32 v92, v88
	v_permlane16_swap_b32_e32 v93, v89
	v_permlane16_swap_b32_e32 v94, v90
	v_permlane16_swap_b32_e32 v95, v91
	v_permlane16_swap_b32_e32 v84, v80
	v_permlane16_swap_b32_e32 v85, v81
	v_permlane16_swap_b32_e32 v86, v82
	v_permlane16_swap_b32_e32 v87, v83
	v_permlane16_swap_b32_e32 v76, v72
	v_permlane16_swap_b32_e32 v77, v73
	v_permlane16_swap_b32_e32 v78, v74
	v_permlane16_swap_b32_e32 v79, v75
	v_permlane16_swap_b32_e32 v68, v64
	v_permlane16_swap_b32_e32 v69, v65
	v_permlane16_swap_b32_e32 v70, v66
	v_permlane16_swap_b32_e32 v71, v67
	v_permlane16_swap_b32_e32 v60, v56
	v_permlane16_swap_b32_e32 v61, v57
	v_permlane16_swap_b32_e32 v62, v58
	v_permlane16_swap_b32_e32 v63, v59
	v_permlane16_swap_b32_e32 v52, v48
	v_permlane16_swap_b32_e32 v53, v49
	v_permlane16_swap_b32_e32 v54, v50
	v_permlane16_swap_b32_e32 v55, v51
	v_permlane16_swap_b32_e32 v44, v40
	v_permlane16_swap_b32_e32 v45, v41
	v_permlane16_swap_b32_e32 v46, v42
	v_permlane16_swap_b32_e32 v47, v43
	v_permlane16_swap_b32_e32 v36, v32
	v_permlane16_swap_b32_e32 v37, v33
	v_permlane16_swap_b32_e32 v38, v34
	v_permlane16_swap_b32_e32 v39, v35
	v_permlane16_swap_b32_e32 v28, v24
	v_permlane16_swap_b32_e32 v29, v25
	v_permlane16_swap_b32_e32 v30, v26
	v_permlane16_swap_b32_e32 v31, v27
	v_permlane16_swap_b32_e32 v20, v16
	v_permlane16_swap_b32_e32 v21, v17
	v_permlane16_swap_b32_e32 v22, v18
	v_permlane16_swap_b32_e32 v23, v19
	v_permlane16_swap_b32_e32 v12, v8
	v_permlane16_swap_b32_e32 v13, v9
	v_permlane16_swap_b32_e32 v14, v10
	v_permlane16_swap_b32_e32 v15, v11
	v_permlane16_swap_b32_e32 v4, v0
	v_permlane16_swap_b32_e32 v5, v1
	v_permlane16_swap_b32_e32 v6, v2
	v_permlane16_swap_b32_e32 v7, v3
	s_waitcnt vmcnt(14)
	v_lshlrev_b32_e32 v244, 16, v140
	v_and_b32_e32 v245, 0xffff0000, v140
	v_fma_f32 v124, v124, 0.5, v244
	v_fma_f32 v125, v125, 0.5, v245
	v_mul_f32_e32 v243, v124, v124
	v_fmac_f32_e32 v243, v125, v125
	v_cvt_pk_bf16_f32 v140, v124, v125
	v_lshlrev_b32_e32 v244, 16, v141
	v_and_b32_e32 v245, 0xffff0000, v141
	v_fma_f32 v126, v126, 0.5, v244
	v_fma_f32 v127, v127, 0.5, v245
	v_fmac_f32_e32 v243, v126, v126
	v_fmac_f32_e32 v243, v127, v127
	v_cvt_pk_bf16_f32 v141, v126, v127
	v_lshlrev_b32_e32 v244, 16, v142
	v_and_b32_e32 v245, 0xffff0000, v142
	v_fma_f32 v120, v120, 0.5, v244
	v_fma_f32 v121, v121, 0.5, v245
	v_fmac_f32_e32 v243, v120, v120
	v_fmac_f32_e32 v243, v121, v121
	v_cvt_pk_bf16_f32 v142, v120, v121
	v_lshlrev_b32_e32 v244, 16, v143
	v_and_b32_e32 v245, 0xffff0000, v143
	v_fma_f32 v122, v122, 0.5, v244
	v_fma_f32 v123, v123, 0.5, v245
	v_fmac_f32_e32 v243, v122, v122
	v_fmac_f32_e32 v243, v123, v123
	v_cvt_pk_bf16_f32 v143, v122, v123
	ds_bpermute_b32 v250, v252, v144
	ds_bpermute_b32 v251, v252, v145
	ds_bpermute_b32 v140, v252, v140
	ds_bpermute_b32 v141, v252, v141
	ds_bpermute_b32 v142, v252, v142
	ds_bpermute_b32 v143, v252, v143
	s_waitcnt lgkmcnt(0)
	global_store_dwordx4 v[250:251], v[140:143], off
	v_lshlrev_b32_e32 v244, 16, v154
	v_and_b32_e32 v245, 0xffff0000, v154
	v_fma_f32 v116, v116, 0.5, v244
	v_fma_f32 v117, v117, 0.5, v245
	v_fmac_f32_e32 v243, v116, v116
	v_fmac_f32_e32 v243, v117, v117
	v_cvt_pk_bf16_f32 v154, v116, v117
	v_lshlrev_b32_e32 v244, 16, v155
	v_and_b32_e32 v245, 0xffff0000, v155
	v_fma_f32 v118, v118, 0.5, v244
	v_fma_f32 v119, v119, 0.5, v245
	v_fmac_f32_e32 v243, v118, v118
	v_fmac_f32_e32 v243, v119, v119
	v_cvt_pk_bf16_f32 v155, v118, v119
	v_lshlrev_b32_e32 v244, 16, v156
	v_and_b32_e32 v245, 0xffff0000, v156
	v_fma_f32 v112, v112, 0.5, v244
	v_fma_f32 v113, v113, 0.5, v245
	v_fmac_f32_e32 v243, v112, v112
	v_fmac_f32_e32 v243, v113, v113
	v_cvt_pk_bf16_f32 v156, v112, v113
	v_lshlrev_b32_e32 v244, 16, v157
	v_and_b32_e32 v245, 0xffff0000, v157
	v_fma_f32 v114, v114, 0.5, v244
	v_fma_f32 v115, v115, 0.5, v245
	v_fmac_f32_e32 v243, v114, v114
	v_fmac_f32_e32 v243, v115, v115
	v_cvt_pk_bf16_f32 v157, v114, v115
	ds_bpermute_b32 v154, v252, v154
	ds_bpermute_b32 v155, v252, v155
	ds_bpermute_b32 v156, v252, v156
	ds_bpermute_b32 v157, v252, v157
	s_waitcnt lgkmcnt(0)
	global_store_dwordx4 v[250:251], v[154:157], off offset:256
	s_waitcnt vmcnt(14)
	s_mov_b32 s100, 0x10000
	v_lshl_add_u64 v[236:237], v[144:145], 0, s[100:101]
	v_lshlrev_b32_e32 v244, 16, v158
	v_and_b32_e32 v245, 0xffff0000, v158
	v_fma_f32 v108, v108, 0.5, v244
	v_fma_f32 v109, v109, 0.5, v245
	v_mul_f32_e32 v124, v108, v108
	v_fmac_f32_e32 v124, v109, v109
	v_cvt_pk_bf16_f32 v158, v108, v109
	v_lshlrev_b32_e32 v244, 16, v159
	v_and_b32_e32 v245, 0xffff0000, v159
	v_fma_f32 v110, v110, 0.5, v244
	v_fma_f32 v111, v111, 0.5, v245
	v_fmac_f32_e32 v124, v110, v110
	v_fmac_f32_e32 v124, v111, v111
	v_cvt_pk_bf16_f32 v159, v110, v111
	v_lshlrev_b32_e32 v244, 16, v160
	v_and_b32_e32 v245, 0xffff0000, v160
	v_fma_f32 v104, v104, 0.5, v244
	v_fma_f32 v105, v105, 0.5, v245
	v_fmac_f32_e32 v124, v104, v104
	v_fmac_f32_e32 v124, v105, v105
	v_cvt_pk_bf16_f32 v160, v104, v105
	v_lshlrev_b32_e32 v244, 16, v161
	v_and_b32_e32 v245, 0xffff0000, v161
	v_fma_f32 v106, v106, 0.5, v244
	v_fma_f32 v107, v107, 0.5, v245
	v_fmac_f32_e32 v124, v106, v106
	v_fmac_f32_e32 v124, v107, v107
	v_cvt_pk_bf16_f32 v161, v106, v107
	ds_bpermute_b32 v250, v252, v236
	ds_bpermute_b32 v251, v252, v237
	ds_bpermute_b32 v158, v252, v158
	ds_bpermute_b32 v159, v252, v159
	ds_bpermute_b32 v160, v252, v160
	ds_bpermute_b32 v161, v252, v161
	s_waitcnt lgkmcnt(0)
	global_store_dwordx4 v[250:251], v[158:161], off
	v_lshlrev_b32_e32 v244, 16, v162
	v_and_b32_e32 v245, 0xffff0000, v162
	v_fma_f32 v100, v100, 0.5, v244
	v_fma_f32 v101, v101, 0.5, v245
	v_fmac_f32_e32 v124, v100, v100
	v_fmac_f32_e32 v124, v101, v101
	v_cvt_pk_bf16_f32 v162, v100, v101
	v_lshlrev_b32_e32 v244, 16, v163
	v_and_b32_e32 v245, 0xffff0000, v163
	v_fma_f32 v102, v102, 0.5, v244
	v_fma_f32 v103, v103, 0.5, v245
	v_fmac_f32_e32 v124, v102, v102
	v_fmac_f32_e32 v124, v103, v103
	v_cvt_pk_bf16_f32 v163, v102, v103
	v_lshlrev_b32_e32 v244, 16, v164
	v_and_b32_e32 v245, 0xffff0000, v164
	v_fma_f32 v96, v96, 0.5, v244
	v_fma_f32 v97, v97, 0.5, v245
	v_fmac_f32_e32 v124, v96, v96
	v_fmac_f32_e32 v124, v97, v97
	v_cvt_pk_bf16_f32 v164, v96, v97
	v_lshlrev_b32_e32 v244, 16, v165
	v_and_b32_e32 v245, 0xffff0000, v165
	v_fma_f32 v98, v98, 0.5, v244
	v_fma_f32 v99, v99, 0.5, v245
	v_fmac_f32_e32 v124, v98, v98
	v_fmac_f32_e32 v124, v99, v99
	v_cvt_pk_bf16_f32 v165, v98, v99
	ds_bpermute_b32 v162, v252, v162
	ds_bpermute_b32 v163, v252, v163
	ds_bpermute_b32 v164, v252, v164
	ds_bpermute_b32 v165, v252, v165
	s_waitcnt lgkmcnt(0)
	global_store_dwordx4 v[250:251], v[162:165], off offset:256
	s_waitcnt vmcnt(14)
	s_mov_b32 s100, 0x20000
	v_lshl_add_u64 v[236:237], v[144:145], 0, s[100:101]
	v_lshlrev_b32_e32 v244, 16, v166
	v_and_b32_e32 v245, 0xffff0000, v166
	v_fma_f32 v92, v92, 0.5, v244
	v_fma_f32 v93, v93, 0.5, v245
	v_mul_f32_e32 v108, v92, v92
	v_fmac_f32_e32 v108, v93, v93
	v_cvt_pk_bf16_f32 v166, v92, v93
	v_lshlrev_b32_e32 v244, 16, v167
	v_and_b32_e32 v245, 0xffff0000, v167
	v_fma_f32 v94, v94, 0.5, v244
	v_fma_f32 v95, v95, 0.5, v245
	v_fmac_f32_e32 v108, v94, v94
	v_fmac_f32_e32 v108, v95, v95
	v_cvt_pk_bf16_f32 v167, v94, v95
	v_lshlrev_b32_e32 v244, 16, v168
	v_and_b32_e32 v245, 0xffff0000, v168
	v_fma_f32 v88, v88, 0.5, v244
	v_fma_f32 v89, v89, 0.5, v245
	v_fmac_f32_e32 v108, v88, v88
	v_fmac_f32_e32 v108, v89, v89
	v_cvt_pk_bf16_f32 v168, v88, v89
	v_lshlrev_b32_e32 v244, 16, v169
	v_and_b32_e32 v245, 0xffff0000, v169
	v_fma_f32 v90, v90, 0.5, v244
	v_fma_f32 v91, v91, 0.5, v245
	v_fmac_f32_e32 v108, v90, v90
	v_fmac_f32_e32 v108, v91, v91
	v_cvt_pk_bf16_f32 v169, v90, v91
	ds_bpermute_b32 v250, v252, v236
	ds_bpermute_b32 v251, v252, v237
	ds_bpermute_b32 v166, v252, v166
	ds_bpermute_b32 v167, v252, v167
	ds_bpermute_b32 v168, v252, v168
	ds_bpermute_b32 v169, v252, v169
	s_waitcnt lgkmcnt(0)
	global_store_dwordx4 v[250:251], v[166:169], off
	v_lshlrev_b32_e32 v244, 16, v170
	v_and_b32_e32 v245, 0xffff0000, v170
	v_fma_f32 v84, v84, 0.5, v244
	v_fma_f32 v85, v85, 0.5, v245
	v_fmac_f32_e32 v108, v84, v84
	v_fmac_f32_e32 v108, v85, v85
	v_cvt_pk_bf16_f32 v170, v84, v85
	v_lshlrev_b32_e32 v244, 16, v171
	v_and_b32_e32 v245, 0xffff0000, v171
	v_fma_f32 v86, v86, 0.5, v244
	v_fma_f32 v87, v87, 0.5, v245
	v_fmac_f32_e32 v108, v86, v86
	v_fmac_f32_e32 v108, v87, v87
	v_cvt_pk_bf16_f32 v171, v86, v87
	v_lshlrev_b32_e32 v244, 16, v172
	v_and_b32_e32 v245, 0xffff0000, v172
	v_fma_f32 v80, v80, 0.5, v244
	v_fma_f32 v81, v81, 0.5, v245
	v_fmac_f32_e32 v108, v80, v80
	v_fmac_f32_e32 v108, v81, v81
	v_cvt_pk_bf16_f32 v172, v80, v81
	v_lshlrev_b32_e32 v244, 16, v173
	v_and_b32_e32 v245, 0xffff0000, v173
	v_fma_f32 v82, v82, 0.5, v244
	v_fma_f32 v83, v83, 0.5, v245
	v_fmac_f32_e32 v108, v82, v82
	v_fmac_f32_e32 v108, v83, v83
	v_cvt_pk_bf16_f32 v173, v82, v83
	ds_bpermute_b32 v170, v252, v170
	ds_bpermute_b32 v171, v252, v171
	ds_bpermute_b32 v172, v252, v172
	ds_bpermute_b32 v173, v252, v173
	s_waitcnt lgkmcnt(0)
	global_store_dwordx4 v[250:251], v[170:173], off offset:256
	s_waitcnt vmcnt(14)
	s_mov_b32 s100, 0x30000
	v_lshl_add_u64 v[236:237], v[144:145], 0, s[100:101]
	v_lshlrev_b32_e32 v244, 16, v174
	v_and_b32_e32 v245, 0xffff0000, v174
	v_fma_f32 v76, v76, 0.5, v244
	v_fma_f32 v77, v77, 0.5, v245
	v_mul_f32_e32 v92, v76, v76
	v_fmac_f32_e32 v92, v77, v77
	v_cvt_pk_bf16_f32 v174, v76, v77
	v_lshlrev_b32_e32 v244, 16, v175
	v_and_b32_e32 v245, 0xffff0000, v175
	v_fma_f32 v78, v78, 0.5, v244
	v_fma_f32 v79, v79, 0.5, v245
	v_fmac_f32_e32 v92, v78, v78
	v_fmac_f32_e32 v92, v79, v79
	v_cvt_pk_bf16_f32 v175, v78, v79
	v_lshlrev_b32_e32 v244, 16, v176
	v_and_b32_e32 v245, 0xffff0000, v176
	v_fma_f32 v72, v72, 0.5, v244
	v_fma_f32 v73, v73, 0.5, v245
	v_fmac_f32_e32 v92, v72, v72
	v_fmac_f32_e32 v92, v73, v73
	v_cvt_pk_bf16_f32 v176, v72, v73
	v_lshlrev_b32_e32 v244, 16, v177
	v_and_b32_e32 v245, 0xffff0000, v177
	v_fma_f32 v74, v74, 0.5, v244
	v_fma_f32 v75, v75, 0.5, v245
	v_fmac_f32_e32 v92, v74, v74
	v_fmac_f32_e32 v92, v75, v75
	v_cvt_pk_bf16_f32 v177, v74, v75
	ds_bpermute_b32 v250, v252, v236
	ds_bpermute_b32 v251, v252, v237
	ds_bpermute_b32 v174, v252, v174
	ds_bpermute_b32 v175, v252, v175
	ds_bpermute_b32 v176, v252, v176
	ds_bpermute_b32 v177, v252, v177
	s_waitcnt lgkmcnt(0)
	global_store_dwordx4 v[250:251], v[174:177], off
	v_lshlrev_b32_e32 v244, 16, v178
	v_and_b32_e32 v245, 0xffff0000, v178
	v_fma_f32 v68, v68, 0.5, v244
	v_fma_f32 v69, v69, 0.5, v245
	v_fmac_f32_e32 v92, v68, v68
	v_fmac_f32_e32 v92, v69, v69
	v_cvt_pk_bf16_f32 v178, v68, v69
	v_lshlrev_b32_e32 v244, 16, v179
	v_and_b32_e32 v245, 0xffff0000, v179
	v_fma_f32 v70, v70, 0.5, v244
	v_fma_f32 v71, v71, 0.5, v245
	v_fmac_f32_e32 v92, v70, v70
	v_fmac_f32_e32 v92, v71, v71
	v_cvt_pk_bf16_f32 v179, v70, v71
	v_lshlrev_b32_e32 v244, 16, v180
	v_and_b32_e32 v245, 0xffff0000, v180
	v_fma_f32 v64, v64, 0.5, v244
	v_fma_f32 v65, v65, 0.5, v245
	v_fmac_f32_e32 v92, v64, v64
	v_fmac_f32_e32 v92, v65, v65
	v_cvt_pk_bf16_f32 v180, v64, v65
	v_lshlrev_b32_e32 v244, 16, v181
	v_and_b32_e32 v245, 0xffff0000, v181
	v_fma_f32 v66, v66, 0.5, v244
	v_fma_f32 v67, v67, 0.5, v245
	v_fmac_f32_e32 v92, v66, v66
	v_fmac_f32_e32 v92, v67, v67
	v_cvt_pk_bf16_f32 v181, v66, v67
	ds_bpermute_b32 v178, v252, v178
	ds_bpermute_b32 v179, v252, v179
	ds_bpermute_b32 v180, v252, v180
	ds_bpermute_b32 v181, v252, v181
	s_waitcnt lgkmcnt(0)
	global_store_dwordx4 v[250:251], v[178:181], off offset:256
	s_waitcnt vmcnt(14)
	s_mov_b32 s100, 0x80000
	v_lshl_add_u64 v[236:237], v[144:145], 0, s[100:101]
	v_lshlrev_b32_e32 v244, 16, v184
	v_and_b32_e32 v245, 0xffff0000, v184
	v_fma_f32 v60, v60, 0.5, v244
	v_fma_f32 v61, v61, 0.5, v245
	v_mul_f32_e32 v76, v60, v60
	v_fmac_f32_e32 v76, v61, v61
	v_cvt_pk_bf16_f32 v184, v60, v61
	v_lshlrev_b32_e32 v244, 16, v185
	v_and_b32_e32 v245, 0xffff0000, v185
	v_fma_f32 v62, v62, 0.5, v244
	v_fma_f32 v63, v63, 0.5, v245
	v_fmac_f32_e32 v76, v62, v62
	v_fmac_f32_e32 v76, v63, v63
	v_cvt_pk_bf16_f32 v185, v62, v63
	v_lshlrev_b32_e32 v244, 16, v186
	v_and_b32_e32 v245, 0xffff0000, v186
	v_fma_f32 v56, v56, 0.5, v244
	v_fma_f32 v57, v57, 0.5, v245
	v_fmac_f32_e32 v76, v56, v56
	v_fmac_f32_e32 v76, v57, v57
	v_cvt_pk_bf16_f32 v186, v56, v57
	v_lshlrev_b32_e32 v244, 16, v187
	v_and_b32_e32 v245, 0xffff0000, v187
	v_fma_f32 v58, v58, 0.5, v244
	v_fma_f32 v59, v59, 0.5, v245
	v_fmac_f32_e32 v76, v58, v58
	v_fmac_f32_e32 v76, v59, v59
	v_cvt_pk_bf16_f32 v187, v58, v59
	ds_bpermute_b32 v250, v252, v236
	ds_bpermute_b32 v251, v252, v237
	ds_bpermute_b32 v184, v252, v184
	ds_bpermute_b32 v185, v252, v185
	ds_bpermute_b32 v186, v252, v186
	ds_bpermute_b32 v187, v252, v187
	s_waitcnt lgkmcnt(0)
	global_store_dwordx4 v[250:251], v[184:187], off
	v_lshlrev_b32_e32 v244, 16, v190
	v_and_b32_e32 v245, 0xffff0000, v190
	v_fma_f32 v52, v52, 0.5, v244
	v_fma_f32 v53, v53, 0.5, v245
	v_fmac_f32_e32 v76, v52, v52
	v_fmac_f32_e32 v76, v53, v53
	v_cvt_pk_bf16_f32 v190, v52, v53
	v_lshlrev_b32_e32 v244, 16, v191
	v_and_b32_e32 v245, 0xffff0000, v191
	v_fma_f32 v54, v54, 0.5, v244
	v_fma_f32 v55, v55, 0.5, v245
	v_fmac_f32_e32 v76, v54, v54
	v_fmac_f32_e32 v76, v55, v55
	v_cvt_pk_bf16_f32 v191, v54, v55
	v_lshlrev_b32_e32 v244, 16, v192
	v_and_b32_e32 v245, 0xffff0000, v192
	v_fma_f32 v48, v48, 0.5, v244
	v_fma_f32 v49, v49, 0.5, v245
	v_fmac_f32_e32 v76, v48, v48
	v_fmac_f32_e32 v76, v49, v49
	v_cvt_pk_bf16_f32 v192, v48, v49
	v_lshlrev_b32_e32 v244, 16, v193
	v_and_b32_e32 v245, 0xffff0000, v193
	v_fma_f32 v50, v50, 0.5, v244
	v_fma_f32 v51, v51, 0.5, v245
	v_fmac_f32_e32 v76, v50, v50
	v_fmac_f32_e32 v76, v51, v51
	v_cvt_pk_bf16_f32 v193, v50, v51
	ds_bpermute_b32 v190, v252, v190
	ds_bpermute_b32 v191, v252, v191
	ds_bpermute_b32 v192, v252, v192
	ds_bpermute_b32 v193, v252, v193
	s_waitcnt lgkmcnt(0)
	global_store_dwordx4 v[250:251], v[190:193], off offset:256
	s_waitcnt vmcnt(14)
	s_mov_b32 s100, 0x90000
	v_lshl_add_u64 v[236:237], v[144:145], 0, s[100:101]
	v_lshlrev_b32_e32 v244, 16, v194
	v_and_b32_e32 v245, 0xffff0000, v194
	v_fma_f32 v44, v44, 0.5, v244
	v_fma_f32 v45, v45, 0.5, v245
	v_mul_f32_e32 v60, v44, v44
	v_fmac_f32_e32 v60, v45, v45
	v_cvt_pk_bf16_f32 v194, v44, v45
	v_lshlrev_b32_e32 v244, 16, v195
	v_and_b32_e32 v245, 0xffff0000, v195
	v_fma_f32 v46, v46, 0.5, v244
	v_fma_f32 v47, v47, 0.5, v245
	v_fmac_f32_e32 v60, v46, v46
	v_fmac_f32_e32 v60, v47, v47
	v_cvt_pk_bf16_f32 v195, v46, v47
	v_lshlrev_b32_e32 v244, 16, v196
	v_and_b32_e32 v245, 0xffff0000, v196
	v_fma_f32 v40, v40, 0.5, v244
	v_fma_f32 v41, v41, 0.5, v245
	v_fmac_f32_e32 v60, v40, v40
	v_fmac_f32_e32 v60, v41, v41
	v_cvt_pk_bf16_f32 v196, v40, v41
	v_lshlrev_b32_e32 v244, 16, v197
	v_and_b32_e32 v245, 0xffff0000, v197
	v_fma_f32 v42, v42, 0.5, v244
	v_fma_f32 v43, v43, 0.5, v245
	v_fmac_f32_e32 v60, v42, v42
	v_fmac_f32_e32 v60, v43, v43
	v_cvt_pk_bf16_f32 v197, v42, v43
	ds_bpermute_b32 v250, v252, v236
	ds_bpermute_b32 v251, v252, v237
	ds_bpermute_b32 v194, v252, v194
	ds_bpermute_b32 v195, v252, v195
	ds_bpermute_b32 v196, v252, v196
	ds_bpermute_b32 v197, v252, v197
	s_waitcnt lgkmcnt(0)
	global_store_dwordx4 v[250:251], v[194:197], off
	v_lshlrev_b32_e32 v244, 16, v198
	v_and_b32_e32 v245, 0xffff0000, v198
	v_fma_f32 v36, v36, 0.5, v244
	v_fma_f32 v37, v37, 0.5, v245
	v_fmac_f32_e32 v60, v36, v36
	v_fmac_f32_e32 v60, v37, v37
	v_cvt_pk_bf16_f32 v198, v36, v37
	v_lshlrev_b32_e32 v244, 16, v199
	v_and_b32_e32 v245, 0xffff0000, v199
	v_fma_f32 v38, v38, 0.5, v244
	v_fma_f32 v39, v39, 0.5, v245
	v_fmac_f32_e32 v60, v38, v38
	v_fmac_f32_e32 v60, v39, v39
	v_cvt_pk_bf16_f32 v199, v38, v39
	v_lshlrev_b32_e32 v244, 16, v200
	v_and_b32_e32 v245, 0xffff0000, v200
	v_fma_f32 v32, v32, 0.5, v244
	v_fma_f32 v33, v33, 0.5, v245
	v_fmac_f32_e32 v60, v32, v32
	v_fmac_f32_e32 v60, v33, v33
	v_cvt_pk_bf16_f32 v200, v32, v33
	v_lshlrev_b32_e32 v244, 16, v201
	v_and_b32_e32 v245, 0xffff0000, v201
	v_fma_f32 v34, v34, 0.5, v244
	v_fma_f32 v35, v35, 0.5, v245
	v_fmac_f32_e32 v60, v34, v34
	v_fmac_f32_e32 v60, v35, v35
	v_cvt_pk_bf16_f32 v201, v34, v35
	ds_bpermute_b32 v198, v252, v198
	ds_bpermute_b32 v199, v252, v199
	ds_bpermute_b32 v200, v252, v200
	ds_bpermute_b32 v201, v252, v201
	s_waitcnt lgkmcnt(0)
	global_store_dwordx4 v[250:251], v[198:201], off offset:256
	s_waitcnt vmcnt(14)
	s_mov_b32 s100, 0xa0000
	v_lshl_add_u64 v[236:237], v[144:145], 0, s[100:101]
	v_lshlrev_b32_e32 v244, 16, v202
	v_and_b32_e32 v245, 0xffff0000, v202
	v_fma_f32 v28, v28, 0.5, v244
	v_fma_f32 v29, v29, 0.5, v245
	v_mul_f32_e32 v44, v28, v28
	v_fmac_f32_e32 v44, v29, v29
	v_cvt_pk_bf16_f32 v202, v28, v29
	v_lshlrev_b32_e32 v244, 16, v203
	v_and_b32_e32 v245, 0xffff0000, v203
	v_fma_f32 v30, v30, 0.5, v244
	v_fma_f32 v31, v31, 0.5, v245
	v_fmac_f32_e32 v44, v30, v30
	v_fmac_f32_e32 v44, v31, v31
	v_cvt_pk_bf16_f32 v203, v30, v31
	v_lshlrev_b32_e32 v244, 16, v204
	v_and_b32_e32 v245, 0xffff0000, v204
	v_fma_f32 v24, v24, 0.5, v244
	v_fma_f32 v25, v25, 0.5, v245
	v_fmac_f32_e32 v44, v24, v24
	v_fmac_f32_e32 v44, v25, v25
	v_cvt_pk_bf16_f32 v204, v24, v25
	v_lshlrev_b32_e32 v244, 16, v205
	v_and_b32_e32 v245, 0xffff0000, v205
	v_fma_f32 v26, v26, 0.5, v244
	v_fma_f32 v27, v27, 0.5, v245
	v_fmac_f32_e32 v44, v26, v26
	v_fmac_f32_e32 v44, v27, v27
	v_cvt_pk_bf16_f32 v205, v26, v27
	ds_bpermute_b32 v250, v252, v236
	ds_bpermute_b32 v251, v252, v237
	ds_bpermute_b32 v202, v252, v202
	ds_bpermute_b32 v203, v252, v203
	ds_bpermute_b32 v204, v252, v204
	ds_bpermute_b32 v205, v252, v205
	s_waitcnt lgkmcnt(0)
	global_store_dwordx4 v[250:251], v[202:205], off
	v_lshlrev_b32_e32 v244, 16, v206
	v_and_b32_e32 v245, 0xffff0000, v206
	v_fma_f32 v20, v20, 0.5, v244
	v_fma_f32 v21, v21, 0.5, v245
	v_fmac_f32_e32 v44, v20, v20
	v_fmac_f32_e32 v44, v21, v21
	v_cvt_pk_bf16_f32 v206, v20, v21
	v_lshlrev_b32_e32 v244, 16, v207
	v_and_b32_e32 v245, 0xffff0000, v207
	v_fma_f32 v22, v22, 0.5, v244
	v_fma_f32 v23, v23, 0.5, v245
	v_fmac_f32_e32 v44, v22, v22
	v_fmac_f32_e32 v44, v23, v23
	v_cvt_pk_bf16_f32 v207, v22, v23
	v_lshlrev_b32_e32 v244, 16, v208
	v_and_b32_e32 v245, 0xffff0000, v208
	v_fma_f32 v16, v16, 0.5, v244
	v_fma_f32 v17, v17, 0.5, v245
	v_fmac_f32_e32 v44, v16, v16
	v_fmac_f32_e32 v44, v17, v17
	v_cvt_pk_bf16_f32 v208, v16, v17
	v_lshlrev_b32_e32 v244, 16, v209
	v_and_b32_e32 v245, 0xffff0000, v209
	v_fma_f32 v18, v18, 0.5, v244
	v_fma_f32 v19, v19, 0.5, v245
	v_fmac_f32_e32 v44, v18, v18
	v_fmac_f32_e32 v44, v19, v19
	v_cvt_pk_bf16_f32 v209, v18, v19
	ds_bpermute_b32 v206, v252, v206
	ds_bpermute_b32 v207, v252, v207
	ds_bpermute_b32 v208, v252, v208
	ds_bpermute_b32 v209, v252, v209
	s_waitcnt lgkmcnt(0)
	global_store_dwordx4 v[250:251], v[206:209], off offset:256
	s_waitcnt vmcnt(14)
	s_mov_b32 s100, 0xb0000
	v_lshl_add_u64 v[236:237], v[144:145], 0, s[100:101]
	v_lshlrev_b32_e32 v244, 16, v210
	v_and_b32_e32 v245, 0xffff0000, v210
	v_fma_f32 v12, v12, 0.5, v244
	v_fma_f32 v13, v13, 0.5, v245
	v_mul_f32_e32 v28, v12, v12
	v_fmac_f32_e32 v28, v13, v13
	v_cvt_pk_bf16_f32 v210, v12, v13
	v_lshlrev_b32_e32 v244, 16, v211
	v_and_b32_e32 v245, 0xffff0000, v211
	v_fma_f32 v14, v14, 0.5, v244
	v_fma_f32 v15, v15, 0.5, v245
	v_fmac_f32_e32 v28, v14, v14
	v_fmac_f32_e32 v28, v15, v15
	v_cvt_pk_bf16_f32 v211, v14, v15
	v_lshlrev_b32_e32 v244, 16, v212
	v_and_b32_e32 v245, 0xffff0000, v212
	v_fma_f32 v8, v8, 0.5, v244
	v_fma_f32 v9, v9, 0.5, v245
	v_fmac_f32_e32 v28, v8, v8
	v_fmac_f32_e32 v28, v9, v9
	v_cvt_pk_bf16_f32 v212, v8, v9
	v_lshlrev_b32_e32 v244, 16, v213
	v_and_b32_e32 v245, 0xffff0000, v213
	v_fma_f32 v10, v10, 0.5, v244
	v_fma_f32 v11, v11, 0.5, v245
	v_fmac_f32_e32 v28, v10, v10
	v_fmac_f32_e32 v28, v11, v11
	v_cvt_pk_bf16_f32 v213, v10, v11
	ds_bpermute_b32 v250, v252, v236
	ds_bpermute_b32 v251, v252, v237
	ds_bpermute_b32 v210, v252, v210
	ds_bpermute_b32 v211, v252, v211
	ds_bpermute_b32 v212, v252, v212
	ds_bpermute_b32 v213, v252, v213
	s_waitcnt lgkmcnt(0)
	global_store_dwordx4 v[250:251], v[210:213], off
	v_lshlrev_b32_e32 v244, 16, v214
	v_and_b32_e32 v245, 0xffff0000, v214
	v_fma_f32 v4, v4, 0.5, v244
	v_fma_f32 v5, v5, 0.5, v245
	v_fmac_f32_e32 v28, v4, v4
	v_fmac_f32_e32 v28, v5, v5
	v_cvt_pk_bf16_f32 v214, v4, v5
	v_lshlrev_b32_e32 v244, 16, v215
	v_and_b32_e32 v245, 0xffff0000, v215
	v_fma_f32 v6, v6, 0.5, v244
	v_fma_f32 v7, v7, 0.5, v245
	v_fmac_f32_e32 v28, v6, v6
	v_fmac_f32_e32 v28, v7, v7
	v_cvt_pk_bf16_f32 v215, v6, v7
	v_lshlrev_b32_e32 v244, 16, v216
	v_and_b32_e32 v245, 0xffff0000, v216
	v_fma_f32 v0, v0, 0.5, v244
	v_fma_f32 v1, v1, 0.5, v245
	v_fmac_f32_e32 v28, v0, v0
	v_fmac_f32_e32 v28, v1, v1
	v_cvt_pk_bf16_f32 v216, v0, v1
	v_lshlrev_b32_e32 v244, 16, v217
	v_and_b32_e32 v245, 0xffff0000, v217
	v_fma_f32 v2, v2, 0.5, v244
	v_fma_f32 v3, v3, 0.5, v245
	v_fmac_f32_e32 v28, v2, v2
	v_fmac_f32_e32 v28, v3, v3
	v_cvt_pk_bf16_f32 v217, v2, v3
	ds_bpermute_b32 v214, v252, v214
	ds_bpermute_b32 v215, v252, v215
	ds_bpermute_b32 v216, v252, v216
	ds_bpermute_b32 v217, v252, v217
	s_waitcnt lgkmcnt(0)
	global_store_dwordx4 v[250:251], v[214:217], off offset:256
	ds_bpermute_b32 v0, v153, v243
	ds_bpermute_b32 v1, v153, v124
	ds_bpermute_b32 v2, v153, v108
	ds_bpermute_b32 v3, v153, v92
	ds_bpermute_b32 v8, v153, v76
	ds_bpermute_b32 v9, v153, v60
	ds_bpermute_b32 v10, v153, v44
	ds_bpermute_b32 v11, v153, v28
	s_waitcnt lgkmcnt(7)
	v_add_f32_e32 v243, v243, v0
	s_waitcnt lgkmcnt(6)
	v_add_f32_e32 v124, v124, v1
	s_waitcnt lgkmcnt(5)
	v_add_f32_e32 v108, v108, v2
	s_waitcnt lgkmcnt(4)
	v_add_f32_e32 v92, v92, v3
	s_waitcnt lgkmcnt(3)
	v_add_f32_e32 v76, v76, v8
	s_waitcnt lgkmcnt(2)
	v_add_f32_e32 v60, v60, v9
	s_waitcnt lgkmcnt(1)
	v_add_f32_e32 v44, v44, v10
	s_waitcnt lgkmcnt(0)
	v_add_f32_e32 v28, v28, v11
	ds_bpermute_b32 v0, v242, v243
	ds_bpermute_b32 v1, v242, v124
	ds_bpermute_b32 v2, v242, v108
	ds_bpermute_b32 v3, v242, v92
	ds_bpermute_b32 v8, v242, v76
	ds_bpermute_b32 v9, v242, v60
	ds_bpermute_b32 v10, v242, v44
	ds_bpermute_b32 v11, v242, v28
	s_waitcnt lgkmcnt(7)
	v_add_f32_e32 v243, v243, v0
	s_waitcnt lgkmcnt(6)
	v_add_f32_e32 v124, v124, v1
	s_waitcnt lgkmcnt(5)
	v_add_f32_e32 v108, v108, v2
	s_waitcnt lgkmcnt(4)
	v_add_f32_e32 v92, v92, v3
	s_waitcnt lgkmcnt(3)
	v_add_f32_e32 v76, v76, v8
	s_waitcnt lgkmcnt(2)
	v_add_f32_e32 v60, v60, v9
	s_waitcnt lgkmcnt(1)
	v_add_f32_e32 v44, v44, v10
	s_waitcnt lgkmcnt(0)
	v_add_f32_e32 v28, v28, v11
	s_and_saveexec_b64 s[20:21], s[4:5]
	v_lshl_add_u64 v[144:145], v[238:239], 3, s[16:17]
	v_mul_f32_e32 v243, 0x4f800000, v243
	v_trunc_f32_e32 v243, v243
	v_mul_f32_e32 v0, 0x2f800000, v243
	v_floor_f32_e32 v0, v0
	v_fmac_f32_e32 v243, 0xcf800000, v0
	v_cvt_u32_f32_e32 v244, v243
	v_cvt_u32_f32_e32 v245, v0
	global_atomic_add_x2 v[144:145], v[244:245], off
	s_nop 1
	v_mul_f32_e32 v124, 0x4f800000, v124
	v_trunc_f32_e32 v124, v124
	v_mul_f32_e32 v1, 0x2f800000, v124
	v_floor_f32_e32 v1, v1
	v_fmac_f32_e32 v124, 0xcf800000, v1
	v_cvt_u32_f32_e32 v244, v124
	v_cvt_u32_f32_e32 v245, v1
	global_atomic_add_x2 v[144:145], v[244:245], off offset:128
	s_nop 1
	v_mul_f32_e32 v108, 0x4f800000, v108
	v_trunc_f32_e32 v108, v108
	v_mul_f32_e32 v2, 0x2f800000, v108
	v_floor_f32_e32 v2, v2
	v_fmac_f32_e32 v108, 0xcf800000, v2
	v_cvt_u32_f32_e32 v244, v108
	v_cvt_u32_f32_e32 v245, v2
	global_atomic_add_x2 v[144:145], v[244:245], off offset:256
	s_nop 1
	v_mul_f32_e32 v92, 0x4f800000, v92
	v_trunc_f32_e32 v92, v92
	v_mul_f32_e32 v3, 0x2f800000, v92
	v_floor_f32_e32 v3, v3
	v_fmac_f32_e32 v92, 0xcf800000, v3
	v_cvt_u32_f32_e32 v244, v92
	v_cvt_u32_f32_e32 v245, v3
	global_atomic_add_x2 v[144:145], v[244:245], off offset:384
	s_nop 1
	v_mul_f32_e32 v76, 0x4f800000, v76
	v_trunc_f32_e32 v76, v76
	v_mul_f32_e32 v8, 0x2f800000, v76
	v_floor_f32_e32 v8, v8
	v_fmac_f32_e32 v76, 0xcf800000, v8
	v_cvt_u32_f32_e32 v244, v76
	v_cvt_u32_f32_e32 v245, v8
	global_atomic_add_x2 v[144:145], v[244:245], off offset:1024
	s_nop 1
	v_mul_f32_e32 v60, 0x4f800000, v60
	v_trunc_f32_e32 v60, v60
	v_mul_f32_e32 v9, 0x2f800000, v60
	v_floor_f32_e32 v9, v9
	v_fmac_f32_e32 v60, 0xcf800000, v9
	v_cvt_u32_f32_e32 v244, v60
	v_cvt_u32_f32_e32 v245, v9
	global_atomic_add_x2 v[144:145], v[244:245], off offset:1152
	s_nop 1
	v_mul_f32_e32 v44, 0x4f800000, v44
	v_trunc_f32_e32 v44, v44
	v_mul_f32_e32 v10, 0x2f800000, v44
	v_floor_f32_e32 v10, v10
	v_fmac_f32_e32 v44, 0xcf800000, v10
	v_cvt_u32_f32_e32 v244, v44
	v_cvt_u32_f32_e32 v245, v10
	global_atomic_add_x2 v[144:145], v[244:245], off offset:1280
	s_nop 1
	v_mul_f32_e32 v28, 0x4f800000, v28
	v_trunc_f32_e32 v28, v28
	v_mul_f32_e32 v11, 0x2f800000, v28
	v_floor_f32_e32 v11, v11
	v_fmac_f32_e32 v28, 0xcf800000, v11
	v_cvt_u32_f32_e32 v244, v28
	v_cvt_u32_f32_e32 v245, v11
	global_atomic_add_x2 v[144:145], v[244:245], off offset:1408
	s_nop 1

.LBB0_2215:
	v_mbcnt_lo_u32_b32 v252, -1, 0
	v_mbcnt_hi_u32_b32 v252, -1, v252
	v_and_b32_e32 v250, 3, v252
	v_lshrrev_b32_e32 v252, 2, v252
	v_lshl_or_b32 v252, v250, 4, v252
	v_lshlrev_b32_e32 v252, 2, v252
	s_mov_b32 s52, s56
	v_lshl_add_u32 v240, s24, 8, v144
	v_and_b32_e32 v242, 0xe0, v146
	v_and_b32_e32 v243, 4, v146
	v_lshl_or_b32 v242, v243, 2, v242
	v_and_b32_e32 v243, 8, v146
	v_or_b32_e32 v242, v242, v243
	v_lshl_or_b32 v242, s26, 8, v242
	v_mov_b32_e32 v243, 0
	v_ashrrev_i32_e32 v241, 31, v240
	v_readlane_b32 s24, v234, 22
	v_readlane_b32 s25, v234, 23
	v_lshlrev_b64 v[246:247], 11, v[240:241]
	v_lshl_add_u64 v[246:247], v[246:247], 0, v[242:243]
	v_lshl_add_u64 v[236:237], v[246:247], 1, s[24:25]
	s_mov_b32 s101, 0
	global_load_dwordx4 v[140:143], v[236:237], off
	global_load_dwordx4 v[154:157], v[236:237], off offset:256
	s_mov_b32 s100, 0x10000
	v_lshl_add_u64 v[238:239], v[236:237], 0, s[100:101]
	global_load_dwordx4 v[158:161], v[238:239], off
	global_load_dwordx4 v[162:165], v[238:239], off offset:256
	s_mov_b32 s100, 0x20000
	v_lshl_add_u64 v[238:239], v[236:237], 0, s[100:101]
	global_load_dwordx4 v[166:169], v[238:239], off
	global_load_dwordx4 v[170:173], v[238:239], off offset:256
	s_mov_b32 s100, 0x30000
	v_lshl_add_u64 v[238:239], v[236:237], 0, s[100:101]
	global_load_dwordx4 v[174:177], v[238:239], off
	global_load_dwordx4 v[178:181], v[238:239], off offset:256
	s_mov_b32 s100, 0x80000
	v_lshl_add_u64 v[238:239], v[236:237], 0, s[100:101]
	global_load_dwordx4 v[184:187], v[238:239], off
	global_load_dwordx4 v[188:191], v[238:239], off offset:256
	s_mov_b32 s100, 0x90000
	v_lshl_add_u64 v[238:239], v[236:237], 0, s[100:101]
	global_load_dwordx4 v[192:195], v[238:239], off
	global_load_dwordx4 v[196:199], v[238:239], off offset:256
	s_mov_b32 s100, 0xa0000
	v_lshl_add_u64 v[238:239], v[236:237], 0, s[100:101]
	global_load_dwordx4 v[200:203], v[238:239], off
	global_load_dwordx4 v[204:207], v[238:239], off offset:256
	s_mov_b32 s100, 0xb0000
	v_lshl_add_u64 v[238:239], v[236:237], 0, s[100:101]
	global_load_dwordx4 v[208:211], v[238:239], off
	global_load_dwordx4 v[212:215], v[238:239], off offset:256
	v_lshlrev_b32_e32 v244, 2, v150
	v_lshlrev_b32_e32 v245, 2, v151
	v_permlane16_swap_b32_e32 v124, v120
	v_permlane16_swap_b32_e32 v125, v121
	v_permlane16_swap_b32_e32 v126, v122
	v_permlane16_swap_b32_e32 v127, v123
	v_permlane16_swap_b32_e32 v116, v112
	v_permlane16_swap_b32_e32 v117, v113
	v_permlane16_swap_b32_e32 v118, v114
	v_permlane16_swap_b32_e32 v119, v115
	v_permlane16_swap_b32_e32 v108, v104
	v_permlane16_swap_b32_e32 v109, v105
	v_permlane16_swap_b32_e32 v110, v106
	v_permlane16_swap_b32_e32 v111, v107
	v_permlane16_swap_b32_e32 v100, v96
	v_permlane16_swap_b32_e32 v101, v97
	v_permlane16_swap_b32_e32 v102, v98
	v_permlane16_swap_b32_e32 v103, v99
	v_permlane16_swap_b32_e32 v92, v88
	v_permlane16_swap_b32_e32 v93, v89
	v_permlane16_swap_b32_e32 v94, v90
	v_permlane16_swap_b32_e32 v95, v91
	v_permlane16_swap_b32_e32 v84, v80
	v_permlane16_swap_b32_e32 v85, v81
	v_permlane16_swap_b32_e32 v86, v82
	v_permlane16_swap_b32_e32 v87, v83
	v_permlane16_swap_b32_e32 v76, v72
	v_permlane16_swap_b32_e32 v77, v73
	v_permlane16_swap_b32_e32 v78, v74
	v_permlane16_swap_b32_e32 v79, v75
	v_permlane16_swap_b32_e32 v68, v64
	v_permlane16_swap_b32_e32 v69, v65
	v_permlane16_swap_b32_e32 v70, v66
	v_permlane16_swap_b32_e32 v71, v67
	v_permlane16_swap_b32_e32 v60, v56
	v_permlane16_swap_b32_e32 v61, v57
	v_permlane16_swap_b32_e32 v62, v58
	v_permlane16_swap_b32_e32 v63, v59
	v_permlane16_swap_b32_e32 v52, v48
	v_permlane16_swap_b32_e32 v53, v49
	v_permlane16_swap_b32_e32 v54, v50
	v_permlane16_swap_b32_e32 v55, v51
	v_permlane16_swap_b32_e32 v44, v40
	v_permlane16_swap_b32_e32 v45, v41
	v_permlane16_swap_b32_e32 v46, v42
	v_permlane16_swap_b32_e32 v47, v43
	v_permlane16_swap_b32_e32 v36, v32
	v_permlane16_swap_b32_e32 v37, v33
	v_permlane16_swap_b32_e32 v38, v34
	v_permlane16_swap_b32_e32 v39, v35
	v_permlane16_swap_b32_e32 v28, v24
	v_permlane16_swap_b32_e32 v29, v25
	v_permlane16_swap_b32_e32 v30, v26
	v_permlane16_swap_b32_e32 v31, v27
	v_permlane16_swap_b32_e32 v20, v16
	v_permlane16_swap_b32_e32 v21, v17
	v_permlane16_swap_b32_e32 v22, v18
	v_permlane16_swap_b32_e32 v23, v19
	v_permlane16_swap_b32_e32 v12, v8
	v_permlane16_swap_b32_e32 v13, v9
	v_permlane16_swap_b32_e32 v14, v10
	v_permlane16_swap_b32_e32 v15, v11
	v_permlane16_swap_b32_e32 v4, v0
	v_permlane16_swap_b32_e32 v5, v1
	v_permlane16_swap_b32_e32 v6, v2
	v_permlane16_swap_b32_e32 v7, v3
	s_waitcnt vmcnt(14)
	v_lshlrev_b32_e32 v246, 16, v140
	v_and_b32_e32 v247, 0xffff0000, v140
	v_add_f32_e32 v124, v124, v246
	v_add_f32_e32 v125, v125, v247
	v_mul_f32_e32 v248, v124, v124
	v_fmac_f32_e32 v248, v125, v125
	v_cvt_pk_bf16_f32 v140, v124, v125
	v_lshlrev_b32_e32 v246, 16, v141
	v_and_b32_e32 v247, 0xffff0000, v141
	v_add_f32_e32 v126, v126, v246
	v_add_f32_e32 v127, v127, v247
	v_fmac_f32_e32 v248, v126, v126
	v_fmac_f32_e32 v248, v127, v127
	v_cvt_pk_bf16_f32 v141, v126, v127
	v_lshlrev_b32_e32 v246, 16, v142
	v_and_b32_e32 v247, 0xffff0000, v142
	v_add_f32_e32 v120, v120, v246
	v_add_f32_e32 v121, v121, v247
	v_fmac_f32_e32 v248, v120, v120
	v_fmac_f32_e32 v248, v121, v121
	v_cvt_pk_bf16_f32 v142, v120, v121
	v_lshlrev_b32_e32 v246, 16, v143
	v_and_b32_e32 v247, 0xffff0000, v143
	v_add_f32_e32 v122, v122, v246
	v_add_f32_e32 v123, v123, v247
	v_fmac_f32_e32 v248, v122, v122
	v_fmac_f32_e32 v248, v123, v123
	v_cvt_pk_bf16_f32 v143, v122, v123
	ds_bpermute_b32 v250, v252, v236
	ds_bpermute_b32 v251, v252, v237
	ds_bpermute_b32 v140, v252, v140
	ds_bpermute_b32 v141, v252, v141
	ds_bpermute_b32 v142, v252, v142
	ds_bpermute_b32 v143, v252, v143
	s_waitcnt lgkmcnt(0)
	global_store_dwordx4 v[250:251], v[140:143], off
	v_lshlrev_b32_e32 v246, 16, v154
	v_and_b32_e32 v247, 0xffff0000, v154
	v_add_f32_e32 v116, v116, v246
	v_add_f32_e32 v117, v117, v247
	v_fmac_f32_e32 v248, v116, v116
	v_fmac_f32_e32 v248, v117, v117
	v_cvt_pk_bf16_f32 v154, v116, v117
	v_lshlrev_b32_e32 v246, 16, v155
	v_and_b32_e32 v247, 0xffff0000, v155
	v_add_f32_e32 v118, v118, v246
	v_add_f32_e32 v119, v119, v247
	v_fmac_f32_e32 v248, v118, v118
	v_fmac_f32_e32 v248, v119, v119
	v_cvt_pk_bf16_f32 v155, v118, v119
	v_lshlrev_b32_e32 v246, 16, v156
	v_and_b32_e32 v247, 0xffff0000, v156
	v_add_f32_e32 v112, v112, v246
	v_add_f32_e32 v113, v113, v247
	v_fmac_f32_e32 v248, v112, v112
	v_fmac_f32_e32 v248, v113, v113
	v_cvt_pk_bf16_f32 v156, v112, v113
	v_lshlrev_b32_e32 v246, 16, v157
	v_and_b32_e32 v247, 0xffff0000, v157
	v_add_f32_e32 v114, v114, v246
	v_add_f32_e32 v115, v115, v247
	v_fmac_f32_e32 v248, v114, v114
	v_fmac_f32_e32 v248, v115, v115
	v_cvt_pk_bf16_f32 v157, v114, v115
	ds_bpermute_b32 v154, v252, v154
	ds_bpermute_b32 v155, v252, v155
	ds_bpermute_b32 v156, v252, v156
	ds_bpermute_b32 v157, v252, v157
	s_waitcnt lgkmcnt(0)
	global_store_dwordx4 v[250:251], v[154:157], off offset:256
	s_waitcnt vmcnt(14)
	s_mov_b32 s100, 0x10000
	v_lshl_add_u64 v[238:239], v[236:237], 0, s[100:101]
	v_lshlrev_b32_e32 v246, 16, v158
	v_and_b32_e32 v247, 0xffff0000, v158
	v_add_f32_e32 v108, v108, v246
	v_add_f32_e32 v109, v109, v247
	v_mul_f32_e32 v124, v108, v108
	v_fmac_f32_e32 v124, v109, v109
	v_cvt_pk_bf16_f32 v158, v108, v109
	v_lshlrev_b32_e32 v246, 16, v159
	v_and_b32_e32 v247, 0xffff0000, v159
	v_add_f32_e32 v110, v110, v246
	v_add_f32_e32 v111, v111, v247
	v_fmac_f32_e32 v124, v110, v110
	v_fmac_f32_e32 v124, v111, v111
	v_cvt_pk_bf16_f32 v159, v110, v111
	v_lshlrev_b32_e32 v246, 16, v160
	v_and_b32_e32 v247, 0xffff0000, v160
	v_add_f32_e32 v104, v104, v246
	v_add_f32_e32 v105, v105, v247
	v_fmac_f32_e32 v124, v104, v104
	v_fmac_f32_e32 v124, v105, v105
	v_cvt_pk_bf16_f32 v160, v104, v105
	v_lshlrev_b32_e32 v246, 16, v161
	v_and_b32_e32 v247, 0xffff0000, v161
	v_add_f32_e32 v106, v106, v246
	v_add_f32_e32 v107, v107, v247
	v_fmac_f32_e32 v124, v106, v106
	v_fmac_f32_e32 v124, v107, v107
	v_cvt_pk_bf16_f32 v161, v106, v107
	ds_bpermute_b32 v250, v252, v238
	ds_bpermute_b32 v251, v252, v239
	ds_bpermute_b32 v158, v252, v158
	ds_bpermute_b32 v159, v252, v159
	ds_bpermute_b32 v160, v252, v160
	ds_bpermute_b32 v161, v252, v161
	s_waitcnt lgkmcnt(0)
	global_store_dwordx4 v[250:251], v[158:161], off
	v_lshlrev_b32_e32 v246, 16, v162
	v_and_b32_e32 v247, 0xffff0000, v162
	v_add_f32_e32 v100, v100, v246
	v_add_f32_e32 v101, v101, v247
	v_fmac_f32_e32 v124, v100, v100
	v_fmac_f32_e32 v124, v101, v101
	v_cvt_pk_bf16_f32 v162, v100, v101
	v_lshlrev_b32_e32 v246, 16, v163
	v_and_b32_e32 v247, 0xffff0000, v163
	v_add_f32_e32 v102, v102, v246
	v_add_f32_e32 v103, v103, v247
	v_fmac_f32_e32 v124, v102, v102
	v_fmac_f32_e32 v124, v103, v103
	v_cvt_pk_bf16_f32 v163, v102, v103
	v_lshlrev_b32_e32 v246, 16, v164
	v_and_b32_e32 v247, 0xffff0000, v164
	v_add_f32_e32 v96, v96, v246
	v_add_f32_e32 v97, v97, v247
	v_fmac_f32_e32 v124, v96, v96
	v_fmac_f32_e32 v124, v97, v97
	v_cvt_pk_bf16_f32 v164, v96, v97
	v_lshlrev_b32_e32 v246, 16, v165
	v_and_b32_e32 v247, 0xffff0000, v165
	v_add_f32_e32 v98, v98, v246
	v_add_f32_e32 v99, v99, v247
	v_fmac_f32_e32 v124, v98, v98
	v_fmac_f32_e32 v124, v99, v99
	v_cvt_pk_bf16_f32 v165, v98, v99
	ds_bpermute_b32 v162, v252, v162
	ds_bpermute_b32 v163, v252, v163
	ds_bpermute_b32 v164, v252, v164
	ds_bpermute_b32 v165, v252, v165
	s_waitcnt lgkmcnt(0)
	global_store_dwordx4 v[250:251], v[162:165], off offset:256
	s_waitcnt vmcnt(14)
	s_mov_b32 s100, 0x20000
	v_lshl_add_u64 v[238:239], v[236:237], 0, s[100:101]
	v_lshlrev_b32_e32 v246, 16, v166
	v_and_b32_e32 v247, 0xffff0000, v166
	v_add_f32_e32 v92, v92, v246
	v_add_f32_e32 v93, v93, v247
	v_mul_f32_e32 v108, v92, v92
	v_fmac_f32_e32 v108, v93, v93
	v_cvt_pk_bf16_f32 v166, v92, v93
	v_lshlrev_b32_e32 v246, 16, v167
	v_and_b32_e32 v247, 0xffff0000, v167
	v_add_f32_e32 v94, v94, v246
	v_add_f32_e32 v95, v95, v247
	v_fmac_f32_e32 v108, v94, v94
	v_fmac_f32_e32 v108, v95, v95
	v_cvt_pk_bf16_f32 v167, v94, v95
	v_lshlrev_b32_e32 v246, 16, v168
	v_and_b32_e32 v247, 0xffff0000, v168
	v_add_f32_e32 v88, v88, v246
	v_add_f32_e32 v89, v89, v247
	v_fmac_f32_e32 v108, v88, v88
	v_fmac_f32_e32 v108, v89, v89
	v_cvt_pk_bf16_f32 v168, v88, v89
	v_lshlrev_b32_e32 v246, 16, v169
	v_and_b32_e32 v247, 0xffff0000, v169
	v_add_f32_e32 v90, v90, v246
	v_add_f32_e32 v91, v91, v247
	v_fmac_f32_e32 v108, v90, v90
	v_fmac_f32_e32 v108, v91, v91
	v_cvt_pk_bf16_f32 v169, v90, v91
	ds_bpermute_b32 v250, v252, v238
	ds_bpermute_b32 v251, v252, v239
	ds_bpermute_b32 v166, v252, v166
	ds_bpermute_b32 v167, v252, v167
	ds_bpermute_b32 v168, v252, v168
	ds_bpermute_b32 v169, v252, v169
	s_waitcnt lgkmcnt(0)
	global_store_dwordx4 v[250:251], v[166:169], off
	v_lshlrev_b32_e32 v246, 16, v170
	v_and_b32_e32 v247, 0xffff0000, v170
	v_add_f32_e32 v84, v84, v246
	v_add_f32_e32 v85, v85, v247
	v_fmac_f32_e32 v108, v84, v84
	v_fmac_f32_e32 v108, v85, v85
	v_cvt_pk_bf16_f32 v170, v84, v85
	v_lshlrev_b32_e32 v246, 16, v171
	v_and_b32_e32 v247, 0xffff0000, v171
	v_add_f32_e32 v86, v86, v246
	v_add_f32_e32 v87, v87, v247
	v_fmac_f32_e32 v108, v86, v86
	v_fmac_f32_e32 v108, v87, v87
	v_cvt_pk_bf16_f32 v171, v86, v87
	v_lshlrev_b32_e32 v246, 16, v172
	v_and_b32_e32 v247, 0xffff0000, v172
	v_add_f32_e32 v80, v80, v246
	v_add_f32_e32 v81, v81, v247
	v_fmac_f32_e32 v108, v80, v80
	v_fmac_f32_e32 v108, v81, v81
	v_cvt_pk_bf16_f32 v172, v80, v81
	v_lshlrev_b32_e32 v246, 16, v173
	v_and_b32_e32 v247, 0xffff0000, v173
	v_add_f32_e32 v82, v82, v246
	v_add_f32_e32 v83, v83, v247
	v_fmac_f32_e32 v108, v82, v82
	v_fmac_f32_e32 v108, v83, v83
	v_cvt_pk_bf16_f32 v173, v82, v83
	ds_bpermute_b32 v170, v252, v170
	ds_bpermute_b32 v171, v252, v171
	ds_bpermute_b32 v172, v252, v172
	ds_bpermute_b32 v173, v252, v173
	s_waitcnt lgkmcnt(0)
	global_store_dwordx4 v[250:251], v[170:173], off offset:256
	s_waitcnt vmcnt(14)
	s_mov_b32 s100, 0x30000
	v_lshl_add_u64 v[238:239], v[236:237], 0, s[100:101]
	v_lshlrev_b32_e32 v246, 16, v174
	v_and_b32_e32 v247, 0xffff0000, v174
	v_add_f32_e32 v76, v76, v246
	v_add_f32_e32 v77, v77, v247
	v_mul_f32_e32 v92, v76, v76
	v_fmac_f32_e32 v92, v77, v77
	v_cvt_pk_bf16_f32 v174, v76, v77
	v_lshlrev_b32_e32 v246, 16, v175
	v_and_b32_e32 v247, 0xffff0000, v175
	v_add_f32_e32 v78, v78, v246
	v_add_f32_e32 v79, v79, v247
	v_fmac_f32_e32 v92, v78, v78
	v_fmac_f32_e32 v92, v79, v79
	v_cvt_pk_bf16_f32 v175, v78, v79
	v_lshlrev_b32_e32 v246, 16, v176
	v_and_b32_e32 v247, 0xffff0000, v176
	v_add_f32_e32 v72, v72, v246
	v_add_f32_e32 v73, v73, v247
	v_fmac_f32_e32 v92, v72, v72
	v_fmac_f32_e32 v92, v73, v73
	v_cvt_pk_bf16_f32 v176, v72, v73
	v_lshlrev_b32_e32 v246, 16, v177
	v_and_b32_e32 v247, 0xffff0000, v177
	v_add_f32_e32 v74, v74, v246
	v_add_f32_e32 v75, v75, v247
	v_fmac_f32_e32 v92, v74, v74
	v_fmac_f32_e32 v92, v75, v75
	v_cvt_pk_bf16_f32 v177, v74, v75
	ds_bpermute_b32 v250, v252, v238
	ds_bpermute_b32 v251, v252, v239
	ds_bpermute_b32 v174, v252, v174
	ds_bpermute_b32 v175, v252, v175
	ds_bpermute_b32 v176, v252, v176
	ds_bpermute_b32 v177, v252, v177
	s_waitcnt lgkmcnt(0)
	global_store_dwordx4 v[250:251], v[174:177], off
	v_lshlrev_b32_e32 v246, 16, v178
	v_and_b32_e32 v247, 0xffff0000, v178
	v_add_f32_e32 v68, v68, v246
	v_add_f32_e32 v69, v69, v247
	v_fmac_f32_e32 v92, v68, v68
	v_fmac_f32_e32 v92, v69, v69
	v_cvt_pk_bf16_f32 v178, v68, v69
	v_lshlrev_b32_e32 v246, 16, v179
	v_and_b32_e32 v247, 0xffff0000, v179
	v_add_f32_e32 v70, v70, v246
	v_add_f32_e32 v71, v71, v247
	v_fmac_f32_e32 v92, v70, v70
	v_fmac_f32_e32 v92, v71, v71
	v_cvt_pk_bf16_f32 v179, v70, v71
	v_lshlrev_b32_e32 v246, 16, v180
	v_and_b32_e32 v247, 0xffff0000, v180
	v_add_f32_e32 v64, v64, v246
	v_add_f32_e32 v65, v65, v247
	v_fmac_f32_e32 v92, v64, v64
	v_fmac_f32_e32 v92, v65, v65
	v_cvt_pk_bf16_f32 v180, v64, v65
	v_lshlrev_b32_e32 v246, 16, v181
	v_and_b32_e32 v247, 0xffff0000, v181
	v_add_f32_e32 v66, v66, v246
	v_add_f32_e32 v67, v67, v247
	v_fmac_f32_e32 v92, v66, v66
	v_fmac_f32_e32 v92, v67, v67
	v_cvt_pk_bf16_f32 v181, v66, v67
	ds_bpermute_b32 v178, v252, v178
	ds_bpermute_b32 v179, v252, v179
	ds_bpermute_b32 v180, v252, v180
	ds_bpermute_b32 v181, v252, v181
	s_waitcnt lgkmcnt(0)
	global_store_dwordx4 v[250:251], v[178:181], off offset:256
	s_waitcnt vmcnt(14)
	s_mov_b32 s100, 0x80000
	v_lshl_add_u64 v[238:239], v[236:237], 0, s[100:101]
	v_lshlrev_b32_e32 v246, 16, v184
	v_and_b32_e32 v247, 0xffff0000, v184
	v_add_f32_e32 v60, v60, v246
	v_add_f32_e32 v61, v61, v247
	v_mul_f32_e32 v76, v60, v60
	v_fmac_f32_e32 v76, v61, v61
	v_cvt_pk_bf16_f32 v184, v60, v61
	v_lshlrev_b32_e32 v246, 16, v185
	v_and_b32_e32 v247, 0xffff0000, v185
	v_add_f32_e32 v62, v62, v246
	v_add_f32_e32 v63, v63, v247
	v_fmac_f32_e32 v76, v62, v62
	v_fmac_f32_e32 v76, v63, v63
	v_cvt_pk_bf16_f32 v185, v62, v63
	v_lshlrev_b32_e32 v246, 16, v186
	v_and_b32_e32 v247, 0xffff0000, v186
	v_add_f32_e32 v56, v56, v246
	v_add_f32_e32 v57, v57, v247
	v_fmac_f32_e32 v76, v56, v56
	v_fmac_f32_e32 v76, v57, v57
	v_cvt_pk_bf16_f32 v186, v56, v57
	v_lshlrev_b32_e32 v246, 16, v187
	v_and_b32_e32 v247, 0xffff0000, v187
	v_add_f32_e32 v58, v58, v246
	v_add_f32_e32 v59, v59, v247
	v_fmac_f32_e32 v76, v58, v58
	v_fmac_f32_e32 v76, v59, v59
	v_cvt_pk_bf16_f32 v187, v58, v59
	ds_bpermute_b32 v250, v252, v238
	ds_bpermute_b32 v251, v252, v239
	ds_bpermute_b32 v184, v252, v184
	ds_bpermute_b32 v185, v252, v185
	ds_bpermute_b32 v186, v252, v186
	ds_bpermute_b32 v187, v252, v187
	s_waitcnt lgkmcnt(0)
	global_store_dwordx4 v[250:251], v[184:187], off
	v_lshlrev_b32_e32 v246, 16, v188
	v_and_b32_e32 v247, 0xffff0000, v188
	v_add_f32_e32 v52, v52, v246
	v_add_f32_e32 v53, v53, v247
	v_fmac_f32_e32 v76, v52, v52
	v_fmac_f32_e32 v76, v53, v53
	v_cvt_pk_bf16_f32 v188, v52, v53
	v_lshlrev_b32_e32 v246, 16, v189
	v_and_b32_e32 v247, 0xffff0000, v189
	v_add_f32_e32 v54, v54, v246
	v_add_f32_e32 v55, v55, v247
	v_fmac_f32_e32 v76, v54, v54
	v_fmac_f32_e32 v76, v55, v55
	v_cvt_pk_bf16_f32 v189, v54, v55
	v_lshlrev_b32_e32 v246, 16, v190
	v_and_b32_e32 v247, 0xffff0000, v190
	v_add_f32_e32 v48, v48, v246
	v_add_f32_e32 v49, v49, v247
	v_fmac_f32_e32 v76, v48, v48
	v_fmac_f32_e32 v76, v49, v49
	v_cvt_pk_bf16_f32 v190, v48, v49
	v_lshlrev_b32_e32 v246, 16, v191
	v_and_b32_e32 v247, 0xffff0000, v191
	v_add_f32_e32 v50, v50, v246
	v_add_f32_e32 v51, v51, v247
	v_fmac_f32_e32 v76, v50, v50
	v_fmac_f32_e32 v76, v51, v51
	v_cvt_pk_bf16_f32 v191, v50, v51
	ds_bpermute_b32 v188, v252, v188
	ds_bpermute_b32 v189, v252, v189
	ds_bpermute_b32 v190, v252, v190
	ds_bpermute_b32 v191, v252, v191
	s_waitcnt lgkmcnt(0)
	global_store_dwordx4 v[250:251], v[188:191], off offset:256
	s_waitcnt vmcnt(14)
	s_mov_b32 s100, 0x90000
	v_lshl_add_u64 v[238:239], v[236:237], 0, s[100:101]
	v_lshlrev_b32_e32 v246, 16, v192
	v_and_b32_e32 v247, 0xffff0000, v192
	v_add_f32_e32 v44, v44, v246
	v_add_f32_e32 v45, v45, v247
	v_mul_f32_e32 v60, v44, v44
	v_fmac_f32_e32 v60, v45, v45
	v_cvt_pk_bf16_f32 v192, v44, v45
	v_lshlrev_b32_e32 v246, 16, v193
	v_and_b32_e32 v247, 0xffff0000, v193
	v_add_f32_e32 v46, v46, v246
	v_add_f32_e32 v47, v47, v247
	v_fmac_f32_e32 v60, v46, v46
	v_fmac_f32_e32 v60, v47, v47
	v_cvt_pk_bf16_f32 v193, v46, v47
	v_lshlrev_b32_e32 v246, 16, v194
	v_and_b32_e32 v247, 0xffff0000, v194
	v_add_f32_e32 v40, v40, v246
	v_add_f32_e32 v41, v41, v247
	v_fmac_f32_e32 v60, v40, v40
	v_fmac_f32_e32 v60, v41, v41
	v_cvt_pk_bf16_f32 v194, v40, v41
	v_lshlrev_b32_e32 v246, 16, v195
	v_and_b32_e32 v247, 0xffff0000, v195
	v_add_f32_e32 v42, v42, v246
	v_add_f32_e32 v43, v43, v247
	v_fmac_f32_e32 v60, v42, v42
	v_fmac_f32_e32 v60, v43, v43
	v_cvt_pk_bf16_f32 v195, v42, v43
	ds_bpermute_b32 v250, v252, v238
	ds_bpermute_b32 v251, v252, v239
	ds_bpermute_b32 v192, v252, v192
	ds_bpermute_b32 v193, v252, v193
	ds_bpermute_b32 v194, v252, v194
	ds_bpermute_b32 v195, v252, v195
	s_waitcnt lgkmcnt(0)
	global_store_dwordx4 v[250:251], v[192:195], off
	v_lshlrev_b32_e32 v246, 16, v196
	v_and_b32_e32 v247, 0xffff0000, v196
	v_add_f32_e32 v36, v36, v246
	v_add_f32_e32 v37, v37, v247
	v_fmac_f32_e32 v60, v36, v36
	v_fmac_f32_e32 v60, v37, v37
	v_cvt_pk_bf16_f32 v196, v36, v37
	v_lshlrev_b32_e32 v246, 16, v197
	v_and_b32_e32 v247, 0xffff0000, v197
	v_add_f32_e32 v38, v38, v246
	v_add_f32_e32 v39, v39, v247
	v_fmac_f32_e32 v60, v38, v38
	v_fmac_f32_e32 v60, v39, v39
	v_cvt_pk_bf16_f32 v197, v38, v39
	v_lshlrev_b32_e32 v246, 16, v198
	v_and_b32_e32 v247, 0xffff0000, v198
	v_add_f32_e32 v32, v32, v246
	v_add_f32_e32 v33, v33, v247
	v_fmac_f32_e32 v60, v32, v32
	v_fmac_f32_e32 v60, v33, v33
	v_cvt_pk_bf16_f32 v198, v32, v33
	v_lshlrev_b32_e32 v246, 16, v199
	v_and_b32_e32 v247, 0xffff0000, v199
	v_add_f32_e32 v34, v34, v246
	v_add_f32_e32 v35, v35, v247
	v_fmac_f32_e32 v60, v34, v34
	v_fmac_f32_e32 v60, v35, v35
	v_cvt_pk_bf16_f32 v199, v34, v35
	ds_bpermute_b32 v196, v252, v196
	ds_bpermute_b32 v197, v252, v197
	ds_bpermute_b32 v198, v252, v198
	ds_bpermute_b32 v199, v252, v199
	s_waitcnt lgkmcnt(0)
	global_store_dwordx4 v[250:251], v[196:199], off offset:256
	s_waitcnt vmcnt(14)
	s_mov_b32 s100, 0xa0000
	v_lshl_add_u64 v[238:239], v[236:237], 0, s[100:101]
	v_lshlrev_b32_e32 v246, 16, v200
	v_and_b32_e32 v247, 0xffff0000, v200
	v_add_f32_e32 v28, v28, v246
	v_add_f32_e32 v29, v29, v247
	v_mul_f32_e32 v44, v28, v28
	v_fmac_f32_e32 v44, v29, v29
	v_cvt_pk_bf16_f32 v200, v28, v29
	v_lshlrev_b32_e32 v246, 16, v201
	v_and_b32_e32 v247, 0xffff0000, v201
	v_add_f32_e32 v30, v30, v246
	v_add_f32_e32 v31, v31, v247
	v_fmac_f32_e32 v44, v30, v30
	v_fmac_f32_e32 v44, v31, v31
	v_cvt_pk_bf16_f32 v201, v30, v31
	v_lshlrev_b32_e32 v246, 16, v202
	v_and_b32_e32 v247, 0xffff0000, v202
	v_add_f32_e32 v24, v24, v246
	v_add_f32_e32 v25, v25, v247
	v_fmac_f32_e32 v44, v24, v24
	v_fmac_f32_e32 v44, v25, v25
	v_cvt_pk_bf16_f32 v202, v24, v25
	v_lshlrev_b32_e32 v246, 16, v203
	v_and_b32_e32 v247, 0xffff0000, v203
	v_add_f32_e32 v26, v26, v246
	v_add_f32_e32 v27, v27, v247
	v_fmac_f32_e32 v44, v26, v26
	v_fmac_f32_e32 v44, v27, v27
	v_cvt_pk_bf16_f32 v203, v26, v27
	ds_bpermute_b32 v250, v252, v238
	ds_bpermute_b32 v251, v252, v239
	ds_bpermute_b32 v200, v252, v200
	ds_bpermute_b32 v201, v252, v201
	ds_bpermute_b32 v202, v252, v202
	ds_bpermute_b32 v203, v252, v203
	s_waitcnt lgkmcnt(0)
	global_store_dwordx4 v[250:251], v[200:203], off
	v_lshlrev_b32_e32 v246, 16, v204
	v_and_b32_e32 v247, 0xffff0000, v204
	v_add_f32_e32 v20, v20, v246
	v_add_f32_e32 v21, v21, v247
	v_fmac_f32_e32 v44, v20, v20
	v_fmac_f32_e32 v44, v21, v21
	v_cvt_pk_bf16_f32 v204, v20, v21
	v_lshlrev_b32_e32 v246, 16, v205
	v_and_b32_e32 v247, 0xffff0000, v205
	v_add_f32_e32 v22, v22, v246
	v_add_f32_e32 v23, v23, v247
	v_fmac_f32_e32 v44, v22, v22
	v_fmac_f32_e32 v44, v23, v23
	v_cvt_pk_bf16_f32 v205, v22, v23
	v_lshlrev_b32_e32 v246, 16, v206
	v_and_b32_e32 v247, 0xffff0000, v206
	v_add_f32_e32 v16, v16, v246
	v_add_f32_e32 v17, v17, v247
	v_fmac_f32_e32 v44, v16, v16
	v_fmac_f32_e32 v44, v17, v17
	v_cvt_pk_bf16_f32 v206, v16, v17
	v_lshlrev_b32_e32 v246, 16, v207
	v_and_b32_e32 v247, 0xffff0000, v207
	v_add_f32_e32 v18, v18, v246
	v_add_f32_e32 v19, v19, v247
	v_fmac_f32_e32 v44, v18, v18
	v_fmac_f32_e32 v44, v19, v19
	v_cvt_pk_bf16_f32 v207, v18, v19
	ds_bpermute_b32 v204, v252, v204
	ds_bpermute_b32 v205, v252, v205
	ds_bpermute_b32 v206, v252, v206
	ds_bpermute_b32 v207, v252, v207
	s_waitcnt lgkmcnt(0)
	global_store_dwordx4 v[250:251], v[204:207], off offset:256
	s_waitcnt vmcnt(14)
	s_mov_b32 s100, 0xb0000
	v_lshl_add_u64 v[238:239], v[236:237], 0, s[100:101]
	v_lshlrev_b32_e32 v246, 16, v208
	v_and_b32_e32 v247, 0xffff0000, v208
	v_add_f32_e32 v12, v12, v246
	v_add_f32_e32 v13, v13, v247
	v_mul_f32_e32 v28, v12, v12
	v_fmac_f32_e32 v28, v13, v13
	v_cvt_pk_bf16_f32 v208, v12, v13
	v_lshlrev_b32_e32 v246, 16, v209
	v_and_b32_e32 v247, 0xffff0000, v209
	v_add_f32_e32 v14, v14, v246
	v_add_f32_e32 v15, v15, v247
	v_fmac_f32_e32 v28, v14, v14
	v_fmac_f32_e32 v28, v15, v15
	v_cvt_pk_bf16_f32 v209, v14, v15
	v_lshlrev_b32_e32 v246, 16, v210
	v_and_b32_e32 v247, 0xffff0000, v210
	v_add_f32_e32 v8, v8, v246
	v_add_f32_e32 v9, v9, v247
	v_fmac_f32_e32 v28, v8, v8
	v_fmac_f32_e32 v28, v9, v9
	v_cvt_pk_bf16_f32 v210, v8, v9
	v_lshlrev_b32_e32 v246, 16, v211
	v_and_b32_e32 v247, 0xffff0000, v211
	v_add_f32_e32 v10, v10, v246
	v_add_f32_e32 v11, v11, v247
	v_fmac_f32_e32 v28, v10, v10
	v_fmac_f32_e32 v28, v11, v11
	v_cvt_pk_bf16_f32 v211, v10, v11
	ds_bpermute_b32 v250, v252, v238
	ds_bpermute_b32 v251, v252, v239
	ds_bpermute_b32 v208, v252, v208
	ds_bpermute_b32 v209, v252, v209
	ds_bpermute_b32 v210, v252, v210
	ds_bpermute_b32 v211, v252, v211
	s_waitcnt lgkmcnt(0)
	global_store_dwordx4 v[250:251], v[208:211], off
	v_lshlrev_b32_e32 v246, 16, v212
	v_and_b32_e32 v247, 0xffff0000, v212
	v_add_f32_e32 v4, v4, v246
	v_add_f32_e32 v5, v5, v247
	v_fmac_f32_e32 v28, v4, v4
	v_fmac_f32_e32 v28, v5, v5
	v_cvt_pk_bf16_f32 v212, v4, v5
	v_lshlrev_b32_e32 v246, 16, v213
	v_and_b32_e32 v247, 0xffff0000, v213
	v_add_f32_e32 v6, v6, v246
	v_add_f32_e32 v7, v7, v247
	v_fmac_f32_e32 v28, v6, v6
	v_fmac_f32_e32 v28, v7, v7
	v_cvt_pk_bf16_f32 v213, v6, v7
	v_lshlrev_b32_e32 v246, 16, v214
	v_and_b32_e32 v247, 0xffff0000, v214
	v_add_f32_e32 v0, v0, v246
	v_add_f32_e32 v1, v1, v247
	v_fmac_f32_e32 v28, v0, v0
	v_fmac_f32_e32 v28, v1, v1
	v_cvt_pk_bf16_f32 v214, v0, v1
	v_lshlrev_b32_e32 v246, 16, v215
	v_and_b32_e32 v247, 0xffff0000, v215
	v_add_f32_e32 v2, v2, v246
	v_add_f32_e32 v3, v3, v247
	v_fmac_f32_e32 v28, v2, v2
	v_fmac_f32_e32 v28, v3, v3
	v_cvt_pk_bf16_f32 v215, v2, v3
	ds_bpermute_b32 v212, v252, v212
	ds_bpermute_b32 v213, v252, v213
	ds_bpermute_b32 v214, v252, v214
	ds_bpermute_b32 v215, v252, v215
	s_waitcnt lgkmcnt(0)
	global_store_dwordx4 v[250:251], v[212:215], off offset:256
	ds_bpermute_b32 v0, v244, v248
	ds_bpermute_b32 v1, v244, v124
	ds_bpermute_b32 v2, v244, v108
	ds_bpermute_b32 v3, v244, v92
	ds_bpermute_b32 v8, v244, v76
	ds_bpermute_b32 v9, v244, v60
	ds_bpermute_b32 v10, v244, v44
	ds_bpermute_b32 v11, v244, v28
	s_waitcnt lgkmcnt(7)
	v_add_f32_e32 v248, v248, v0
	s_waitcnt lgkmcnt(6)
	v_add_f32_e32 v124, v124, v1
	s_waitcnt lgkmcnt(5)
	v_add_f32_e32 v108, v108, v2
	s_waitcnt lgkmcnt(4)
	v_add_f32_e32 v92, v92, v3
	s_waitcnt lgkmcnt(3)
	v_add_f32_e32 v76, v76, v8
	s_waitcnt lgkmcnt(2)
	v_add_f32_e32 v60, v60, v9
	s_waitcnt lgkmcnt(1)
	v_add_f32_e32 v44, v44, v10
	s_waitcnt lgkmcnt(0)
	v_add_f32_e32 v28, v28, v11
	ds_bpermute_b32 v0, v245, v248
	ds_bpermute_b32 v1, v245, v124
	ds_bpermute_b32 v2, v245, v108
	ds_bpermute_b32 v3, v245, v92
	ds_bpermute_b32 v8, v245, v76
	ds_bpermute_b32 v9, v245, v60
	ds_bpermute_b32 v10, v245, v44
	ds_bpermute_b32 v11, v245, v28
	s_waitcnt lgkmcnt(7)
	v_add_f32_e32 v248, v248, v0
	s_waitcnt lgkmcnt(6)
	v_add_f32_e32 v124, v124, v1
	s_waitcnt lgkmcnt(5)
	v_add_f32_e32 v108, v108, v2
	s_waitcnt lgkmcnt(4)
	v_add_f32_e32 v92, v92, v3
	s_waitcnt lgkmcnt(3)
	v_add_f32_e32 v76, v76, v8
	s_waitcnt lgkmcnt(2)
	v_add_f32_e32 v60, v60, v9
	s_waitcnt lgkmcnt(1)
	v_add_f32_e32 v44, v44, v10
	s_waitcnt lgkmcnt(0)
	v_add_f32_e32 v28, v28, v11
	s_and_saveexec_b64 s[24:25], s[6:7]
	v_lshl_add_u64 v[236:237], v[240:241], 3, s[4:5]
	v_mul_f32_e32 v248, 0x4f800000, v248
	v_trunc_f32_e32 v248, v248
	v_mul_f32_e32 v0, 0x2f800000, v248
	v_floor_f32_e32 v0, v0
	v_fmac_f32_e32 v248, 0xcf800000, v0
	v_cvt_u32_f32_e32 v246, v248
	v_cvt_u32_f32_e32 v247, v0
	global_atomic_add_x2 v[236:237], v[246:247], off
	s_nop 1
	v_mul_f32_e32 v124, 0x4f800000, v124
	v_trunc_f32_e32 v124, v124
	v_mul_f32_e32 v1, 0x2f800000, v124
	v_floor_f32_e32 v1, v1
	v_fmac_f32_e32 v124, 0xcf800000, v1
	v_cvt_u32_f32_e32 v246, v124
	v_cvt_u32_f32_e32 v247, v1
	global_atomic_add_x2 v[236:237], v[246:247], off offset:128
	s_nop 1
	v_mul_f32_e32 v108, 0x4f800000, v108
	v_trunc_f32_e32 v108, v108
	v_mul_f32_e32 v2, 0x2f800000, v108
	v_floor_f32_e32 v2, v2
	v_fmac_f32_e32 v108, 0xcf800000, v2
	v_cvt_u32_f32_e32 v246, v108
	v_cvt_u32_f32_e32 v247, v2
	global_atomic_add_x2 v[236:237], v[246:247], off offset:256
	s_nop 1
	v_mul_f32_e32 v92, 0x4f800000, v92
	v_trunc_f32_e32 v92, v92
	v_mul_f32_e32 v3, 0x2f800000, v92
	v_floor_f32_e32 v3, v3
	v_fmac_f32_e32 v92, 0xcf800000, v3
	v_cvt_u32_f32_e32 v246, v92
	v_cvt_u32_f32_e32 v247, v3
	global_atomic_add_x2 v[236:237], v[246:247], off offset:384
	s_nop 1
	v_mul_f32_e32 v76, 0x4f800000, v76
	v_trunc_f32_e32 v76, v76
	v_mul_f32_e32 v8, 0x2f800000, v76
	v_floor_f32_e32 v8, v8
	v_fmac_f32_e32 v76, 0xcf800000, v8
	v_cvt_u32_f32_e32 v246, v76
	v_cvt_u32_f32_e32 v247, v8
	global_atomic_add_x2 v[236:237], v[246:247], off offset:1024
	s_nop 1
	v_mul_f32_e32 v60, 0x4f800000, v60
	v_trunc_f32_e32 v60, v60
	v_mul_f32_e32 v9, 0x2f800000, v60
	v_floor_f32_e32 v9, v9
	v_fmac_f32_e32 v60, 0xcf800000, v9
	v_cvt_u32_f32_e32 v246, v60
	v_cvt_u32_f32_e32 v247, v9
	global_atomic_add_x2 v[236:237], v[246:247], off offset:1152
	s_nop 1
	v_mul_f32_e32 v44, 0x4f800000, v44
	v_trunc_f32_e32 v44, v44
	v_mul_f32_e32 v10, 0x2f800000, v44
	v_floor_f32_e32 v10, v10
	v_fmac_f32_e32 v44, 0xcf800000, v10
	v_cvt_u32_f32_e32 v246, v44
	v_cvt_u32_f32_e32 v247, v10
	global_atomic_add_x2 v[236:237], v[246:247], off offset:1280
	s_nop 1
	v_mul_f32_e32 v28, 0x4f800000, v28
	v_trunc_f32_e32 v28, v28
	v_mul_f32_e32 v11, 0x2f800000, v28
	v_floor_f32_e32 v11, v11
	v_fmac_f32_e32 v28, 0xcf800000, v11
	v_cvt_u32_f32_e32 v246, v28
	v_cvt_u32_f32_e32 v247, v11
	global_atomic_add_x2 v[236:237], v[246:247], off offset:1408
	s_nop 1

.LBB0_2396:
	v_mbcnt_lo_u32_b32 v252, -1, 0
	v_mbcnt_hi_u32_b32 v252, -1, v252
	v_and_b32_e32 v250, 3, v252
	v_lshrrev_b32_e32 v252, 2, v252
	v_lshl_or_b32 v252, v250, 4, v252
	v_lshlrev_b32_e32 v252, 2, v252
	v_lshl_add_u32 v240, s42, 8, v144
	v_and_b32_e32 v242, 0xe0, v146
	v_and_b32_e32 v243, 4, v146
	v_lshl_or_b32 v242, v243, 2, v242
	v_and_b32_e32 v243, 8, v146
	v_or_b32_e32 v242, v242, v243
	v_lshl_or_b32 v242, s43, 8, v242
	v_mov_b32_e32 v243, 0
	v_ashrrev_i32_e32 v241, 31, v240
	v_readlane_b32 s18, v234, 22
	v_readlane_b32 s19, v234, 23
	v_lshlrev_b64 v[246:247], 11, v[240:241]
	v_lshl_add_u64 v[246:247], v[246:247], 0, v[242:243]
	v_lshl_add_u64 v[236:237], v[246:247], 1, s[18:19]
	s_mov_b32 s101, 0
	global_load_dwordx4 v[140:143], v[236:237], off
	global_load_dwordx4 v[154:157], v[236:237], off offset:256
	s_mov_b32 s100, 0x10000
	v_lshl_add_u64 v[238:239], v[236:237], 0, s[100:101]
	global_load_dwordx4 v[158:161], v[238:239], off
	global_load_dwordx4 v[162:165], v[238:239], off offset:256
	s_mov_b32 s100, 0x20000
	v_lshl_add_u64 v[238:239], v[236:237], 0, s[100:101]
	global_load_dwordx4 v[166:169], v[238:239], off
	global_load_dwordx4 v[170:173], v[238:239], off offset:256
	s_mov_b32 s100, 0x30000
	v_lshl_add_u64 v[238:239], v[236:237], 0, s[100:101]
	global_load_dwordx4 v[174:177], v[238:239], off
	global_load_dwordx4 v[178:181], v[238:239], off offset:256
	s_mov_b32 s100, 0x80000
	v_lshl_add_u64 v[238:239], v[236:237], 0, s[100:101]
	global_load_dwordx4 v[184:187], v[238:239], off
	global_load_dwordx4 v[188:191], v[238:239], off offset:256
	s_mov_b32 s100, 0x90000
	v_lshl_add_u64 v[238:239], v[236:237], 0, s[100:101]
	global_load_dwordx4 v[192:195], v[238:239], off
	global_load_dwordx4 v[196:199], v[238:239], off offset:256
	s_mov_b32 s100, 0xa0000
	v_lshl_add_u64 v[238:239], v[236:237], 0, s[100:101]
	global_load_dwordx4 v[200:203], v[238:239], off
	global_load_dwordx4 v[204:207], v[238:239], off offset:256
	s_mov_b32 s100, 0xb0000
	v_lshl_add_u64 v[238:239], v[236:237], 0, s[100:101]
	global_load_dwordx4 v[208:211], v[238:239], off
	global_load_dwordx4 v[212:215], v[238:239], off offset:256
	v_lshlrev_b32_e32 v244, 2, v150
	v_lshlrev_b32_e32 v245, 2, v151
	v_permlane16_swap_b32_e32 v124, v120
	v_permlane16_swap_b32_e32 v125, v121
	v_permlane16_swap_b32_e32 v126, v122
	v_permlane16_swap_b32_e32 v127, v123
	v_permlane16_swap_b32_e32 v116, v112
	v_permlane16_swap_b32_e32 v117, v113
	v_permlane16_swap_b32_e32 v118, v114
	v_permlane16_swap_b32_e32 v119, v115
	v_permlane16_swap_b32_e32 v108, v104
	v_permlane16_swap_b32_e32 v109, v105
	v_permlane16_swap_b32_e32 v110, v106
	v_permlane16_swap_b32_e32 v111, v107
	v_permlane16_swap_b32_e32 v100, v96
	v_permlane16_swap_b32_e32 v101, v97
	v_permlane16_swap_b32_e32 v102, v98
	v_permlane16_swap_b32_e32 v103, v99
	v_permlane16_swap_b32_e32 v92, v88
	v_permlane16_swap_b32_e32 v93, v89
	v_permlane16_swap_b32_e32 v94, v90
	v_permlane16_swap_b32_e32 v95, v91
	v_permlane16_swap_b32_e32 v84, v80
	v_permlane16_swap_b32_e32 v85, v81
	v_permlane16_swap_b32_e32 v86, v82
	v_permlane16_swap_b32_e32 v87, v83
	v_permlane16_swap_b32_e32 v76, v72
	v_permlane16_swap_b32_e32 v77, v73
	v_permlane16_swap_b32_e32 v78, v74
	v_permlane16_swap_b32_e32 v79, v75
	v_permlane16_swap_b32_e32 v68, v64
	v_permlane16_swap_b32_e32 v69, v65
	v_permlane16_swap_b32_e32 v70, v66
	v_permlane16_swap_b32_e32 v71, v67
	v_permlane16_swap_b32_e32 v60, v56
	v_permlane16_swap_b32_e32 v61, v57
	v_permlane16_swap_b32_e32 v62, v58
	v_permlane16_swap_b32_e32 v63, v59
	v_permlane16_swap_b32_e32 v52, v48
	v_permlane16_swap_b32_e32 v53, v49
	v_permlane16_swap_b32_e32 v54, v50
	v_permlane16_swap_b32_e32 v55, v51
	v_permlane16_swap_b32_e32 v44, v40
	v_permlane16_swap_b32_e32 v45, v41
	v_permlane16_swap_b32_e32 v46, v42
	v_permlane16_swap_b32_e32 v47, v43
	v_permlane16_swap_b32_e32 v36, v32
	v_permlane16_swap_b32_e32 v37, v33
	v_permlane16_swap_b32_e32 v38, v34
	v_permlane16_swap_b32_e32 v39, v35
	v_permlane16_swap_b32_e32 v28, v24
	v_permlane16_swap_b32_e32 v29, v25
	v_permlane16_swap_b32_e32 v30, v26
	v_permlane16_swap_b32_e32 v31, v27
	v_permlane16_swap_b32_e32 v20, v16
	v_permlane16_swap_b32_e32 v21, v17
	v_permlane16_swap_b32_e32 v22, v18
	v_permlane16_swap_b32_e32 v23, v19
	v_permlane16_swap_b32_e32 v12, v8
	v_permlane16_swap_b32_e32 v13, v9
	v_permlane16_swap_b32_e32 v14, v10
	v_permlane16_swap_b32_e32 v15, v11
	v_permlane16_swap_b32_e32 v4, v0
	v_permlane16_swap_b32_e32 v5, v1
	v_permlane16_swap_b32_e32 v6, v2
	v_permlane16_swap_b32_e32 v7, v3
	s_waitcnt vmcnt(14)
	v_lshlrev_b32_e32 v246, 16, v140
	v_and_b32_e32 v247, 0xffff0000, v140
	v_fma_f32 v124, v124, 0.5, v246
	v_fma_f32 v125, v125, 0.5, v247
	v_mul_f32_e32 v248, v124, v124
	v_fmac_f32_e32 v248, v125, v125
	v_cvt_pk_bf16_f32 v140, v124, v125
	v_lshlrev_b32_e32 v246, 16, v141
	v_and_b32_e32 v247, 0xffff0000, v141
	v_fma_f32 v126, v126, 0.5, v246
	v_fma_f32 v127, v127, 0.5, v247
	v_fmac_f32_e32 v248, v126, v126
	v_fmac_f32_e32 v248, v127, v127
	v_cvt_pk_bf16_f32 v141, v126, v127
	v_lshlrev_b32_e32 v246, 16, v142
	v_and_b32_e32 v247, 0xffff0000, v142
	v_fma_f32 v120, v120, 0.5, v246
	v_fma_f32 v121, v121, 0.5, v247
	v_fmac_f32_e32 v248, v120, v120
	v_fmac_f32_e32 v248, v121, v121
	v_cvt_pk_bf16_f32 v142, v120, v121
	v_lshlrev_b32_e32 v246, 16, v143
	v_and_b32_e32 v247, 0xffff0000, v143
	v_fma_f32 v122, v122, 0.5, v246
	v_fma_f32 v123, v123, 0.5, v247
	v_fmac_f32_e32 v248, v122, v122
	v_fmac_f32_e32 v248, v123, v123
	v_cvt_pk_bf16_f32 v143, v122, v123
	ds_bpermute_b32 v250, v252, v236
	ds_bpermute_b32 v251, v252, v237
	ds_bpermute_b32 v140, v252, v140
	ds_bpermute_b32 v141, v252, v141
	ds_bpermute_b32 v142, v252, v142
	ds_bpermute_b32 v143, v252, v143
	s_waitcnt lgkmcnt(0)
	global_store_dwordx4 v[250:251], v[140:143], off
	v_lshlrev_b32_e32 v246, 16, v154
	v_and_b32_e32 v247, 0xffff0000, v154
	v_fma_f32 v116, v116, 0.5, v246
	v_fma_f32 v117, v117, 0.5, v247
	v_fmac_f32_e32 v248, v116, v116
	v_fmac_f32_e32 v248, v117, v117
	v_cvt_pk_bf16_f32 v154, v116, v117
	v_lshlrev_b32_e32 v246, 16, v155
	v_and_b32_e32 v247, 0xffff0000, v155
	v_fma_f32 v118, v118, 0.5, v246
	v_fma_f32 v119, v119, 0.5, v247
	v_fmac_f32_e32 v248, v118, v118
	v_fmac_f32_e32 v248, v119, v119
	v_cvt_pk_bf16_f32 v155, v118, v119
	v_lshlrev_b32_e32 v246, 16, v156
	v_and_b32_e32 v247, 0xffff0000, v156
	v_fma_f32 v112, v112, 0.5, v246
	v_fma_f32 v113, v113, 0.5, v247
	v_fmac_f32_e32 v248, v112, v112
	v_fmac_f32_e32 v248, v113, v113
	v_cvt_pk_bf16_f32 v156, v112, v113
	v_lshlrev_b32_e32 v246, 16, v157
	v_and_b32_e32 v247, 0xffff0000, v157
	v_fma_f32 v114, v114, 0.5, v246
	v_fma_f32 v115, v115, 0.5, v247
	v_fmac_f32_e32 v248, v114, v114
	v_fmac_f32_e32 v248, v115, v115
	v_cvt_pk_bf16_f32 v157, v114, v115
	ds_bpermute_b32 v154, v252, v154
	ds_bpermute_b32 v155, v252, v155
	ds_bpermute_b32 v156, v252, v156
	ds_bpermute_b32 v157, v252, v157
	s_waitcnt lgkmcnt(0)
	global_store_dwordx4 v[250:251], v[154:157], off offset:256
	s_waitcnt vmcnt(14)
	s_mov_b32 s100, 0x10000
	v_lshl_add_u64 v[238:239], v[236:237], 0, s[100:101]
	v_lshlrev_b32_e32 v246, 16, v158
	v_and_b32_e32 v247, 0xffff0000, v158
	v_fma_f32 v108, v108, 0.5, v246
	v_fma_f32 v109, v109, 0.5, v247
	v_mul_f32_e32 v124, v108, v108
	v_fmac_f32_e32 v124, v109, v109
	v_cvt_pk_bf16_f32 v158, v108, v109
	v_lshlrev_b32_e32 v246, 16, v159
	v_and_b32_e32 v247, 0xffff0000, v159
	v_fma_f32 v110, v110, 0.5, v246
	v_fma_f32 v111, v111, 0.5, v247
	v_fmac_f32_e32 v124, v110, v110
	v_fmac_f32_e32 v124, v111, v111
	v_cvt_pk_bf16_f32 v159, v110, v111
	v_lshlrev_b32_e32 v246, 16, v160
	v_and_b32_e32 v247, 0xffff0000, v160
	v_fma_f32 v104, v104, 0.5, v246
	v_fma_f32 v105, v105, 0.5, v247
	v_fmac_f32_e32 v124, v104, v104
	v_fmac_f32_e32 v124, v105, v105
	v_cvt_pk_bf16_f32 v160, v104, v105
	v_lshlrev_b32_e32 v246, 16, v161
	v_and_b32_e32 v247, 0xffff0000, v161
	v_fma_f32 v106, v106, 0.5, v246
	v_fma_f32 v107, v107, 0.5, v247
	v_fmac_f32_e32 v124, v106, v106
	v_fmac_f32_e32 v124, v107, v107
	v_cvt_pk_bf16_f32 v161, v106, v107
	ds_bpermute_b32 v250, v252, v238
	ds_bpermute_b32 v251, v252, v239
	ds_bpermute_b32 v158, v252, v158
	ds_bpermute_b32 v159, v252, v159
	ds_bpermute_b32 v160, v252, v160
	ds_bpermute_b32 v161, v252, v161
	s_waitcnt lgkmcnt(0)
	global_store_dwordx4 v[250:251], v[158:161], off
	v_lshlrev_b32_e32 v246, 16, v162
	v_and_b32_e32 v247, 0xffff0000, v162
	v_fma_f32 v100, v100, 0.5, v246
	v_fma_f32 v101, v101, 0.5, v247
	v_fmac_f32_e32 v124, v100, v100
	v_fmac_f32_e32 v124, v101, v101
	v_cvt_pk_bf16_f32 v162, v100, v101
	v_lshlrev_b32_e32 v246, 16, v163
	v_and_b32_e32 v247, 0xffff0000, v163
	v_fma_f32 v102, v102, 0.5, v246
	v_fma_f32 v103, v103, 0.5, v247
	v_fmac_f32_e32 v124, v102, v102
	v_fmac_f32_e32 v124, v103, v103
	v_cvt_pk_bf16_f32 v163, v102, v103
	v_lshlrev_b32_e32 v246, 16, v164
	v_and_b32_e32 v247, 0xffff0000, v164
	v_fma_f32 v96, v96, 0.5, v246
	v_fma_f32 v97, v97, 0.5, v247
	v_fmac_f32_e32 v124, v96, v96
	v_fmac_f32_e32 v124, v97, v97
	v_cvt_pk_bf16_f32 v164, v96, v97
	v_lshlrev_b32_e32 v246, 16, v165
	v_and_b32_e32 v247, 0xffff0000, v165
	v_fma_f32 v98, v98, 0.5, v246
	v_fma_f32 v99, v99, 0.5, v247
	v_fmac_f32_e32 v124, v98, v98
	v_fmac_f32_e32 v124, v99, v99
	v_cvt_pk_bf16_f32 v165, v98, v99
	ds_bpermute_b32 v162, v252, v162
	ds_bpermute_b32 v163, v252, v163
	ds_bpermute_b32 v164, v252, v164
	ds_bpermute_b32 v165, v252, v165
	s_waitcnt lgkmcnt(0)
	global_store_dwordx4 v[250:251], v[162:165], off offset:256
	s_waitcnt vmcnt(14)
	s_mov_b32 s100, 0x20000
	v_lshl_add_u64 v[238:239], v[236:237], 0, s[100:101]
	v_lshlrev_b32_e32 v246, 16, v166
	v_and_b32_e32 v247, 0xffff0000, v166
	v_fma_f32 v92, v92, 0.5, v246
	v_fma_f32 v93, v93, 0.5, v247
	v_mul_f32_e32 v108, v92, v92
	v_fmac_f32_e32 v108, v93, v93
	v_cvt_pk_bf16_f32 v166, v92, v93
	v_lshlrev_b32_e32 v246, 16, v167
	v_and_b32_e32 v247, 0xffff0000, v167
	v_fma_f32 v94, v94, 0.5, v246
	v_fma_f32 v95, v95, 0.5, v247
	v_fmac_f32_e32 v108, v94, v94
	v_fmac_f32_e32 v108, v95, v95
	v_cvt_pk_bf16_f32 v167, v94, v95
	v_lshlrev_b32_e32 v246, 16, v168
	v_and_b32_e32 v247, 0xffff0000, v168
	v_fma_f32 v88, v88, 0.5, v246
	v_fma_f32 v89, v89, 0.5, v247
	v_fmac_f32_e32 v108, v88, v88
	v_fmac_f32_e32 v108, v89, v89
	v_cvt_pk_bf16_f32 v168, v88, v89
	v_lshlrev_b32_e32 v246, 16, v169
	v_and_b32_e32 v247, 0xffff0000, v169
	v_fma_f32 v90, v90, 0.5, v246
	v_fma_f32 v91, v91, 0.5, v247
	v_fmac_f32_e32 v108, v90, v90
	v_fmac_f32_e32 v108, v91, v91
	v_cvt_pk_bf16_f32 v169, v90, v91
	ds_bpermute_b32 v250, v252, v238
	ds_bpermute_b32 v251, v252, v239
	ds_bpermute_b32 v166, v252, v166
	ds_bpermute_b32 v167, v252, v167
	ds_bpermute_b32 v168, v252, v168
	ds_bpermute_b32 v169, v252, v169
	s_waitcnt lgkmcnt(0)
	global_store_dwordx4 v[250:251], v[166:169], off
	v_lshlrev_b32_e32 v246, 16, v170
	v_and_b32_e32 v247, 0xffff0000, v170
	v_fma_f32 v84, v84, 0.5, v246
	v_fma_f32 v85, v85, 0.5, v247
	v_fmac_f32_e32 v108, v84, v84
	v_fmac_f32_e32 v108, v85, v85
	v_cvt_pk_bf16_f32 v170, v84, v85
	v_lshlrev_b32_e32 v246, 16, v171
	v_and_b32_e32 v247, 0xffff0000, v171
	v_fma_f32 v86, v86, 0.5, v246
	v_fma_f32 v87, v87, 0.5, v247
	v_fmac_f32_e32 v108, v86, v86
	v_fmac_f32_e32 v108, v87, v87
	v_cvt_pk_bf16_f32 v171, v86, v87
	v_lshlrev_b32_e32 v246, 16, v172
	v_and_b32_e32 v247, 0xffff0000, v172
	v_fma_f32 v80, v80, 0.5, v246
	v_fma_f32 v81, v81, 0.5, v247
	v_fmac_f32_e32 v108, v80, v80
	v_fmac_f32_e32 v108, v81, v81
	v_cvt_pk_bf16_f32 v172, v80, v81
	v_lshlrev_b32_e32 v246, 16, v173
	v_and_b32_e32 v247, 0xffff0000, v173
	v_fma_f32 v82, v82, 0.5, v246
	v_fma_f32 v83, v83, 0.5, v247
	v_fmac_f32_e32 v108, v82, v82
	v_fmac_f32_e32 v108, v83, v83
	v_cvt_pk_bf16_f32 v173, v82, v83
	ds_bpermute_b32 v170, v252, v170
	ds_bpermute_b32 v171, v252, v171
	ds_bpermute_b32 v172, v252, v172
	ds_bpermute_b32 v173, v252, v173
	s_waitcnt lgkmcnt(0)
	global_store_dwordx4 v[250:251], v[170:173], off offset:256
	s_waitcnt vmcnt(14)
	s_mov_b32 s100, 0x30000
	v_lshl_add_u64 v[238:239], v[236:237], 0, s[100:101]
	v_lshlrev_b32_e32 v246, 16, v174
	v_and_b32_e32 v247, 0xffff0000, v174
	v_fma_f32 v76, v76, 0.5, v246
	v_fma_f32 v77, v77, 0.5, v247
	v_mul_f32_e32 v92, v76, v76
	v_fmac_f32_e32 v92, v77, v77
	v_cvt_pk_bf16_f32 v174, v76, v77
	v_lshlrev_b32_e32 v246, 16, v175
	v_and_b32_e32 v247, 0xffff0000, v175
	v_fma_f32 v78, v78, 0.5, v246
	v_fma_f32 v79, v79, 0.5, v247
	v_fmac_f32_e32 v92, v78, v78
	v_fmac_f32_e32 v92, v79, v79
	v_cvt_pk_bf16_f32 v175, v78, v79
	v_lshlrev_b32_e32 v246, 16, v176
	v_and_b32_e32 v247, 0xffff0000, v176
	v_fma_f32 v72, v72, 0.5, v246
	v_fma_f32 v73, v73, 0.5, v247
	v_fmac_f32_e32 v92, v72, v72
	v_fmac_f32_e32 v92, v73, v73
	v_cvt_pk_bf16_f32 v176, v72, v73
	v_lshlrev_b32_e32 v246, 16, v177
	v_and_b32_e32 v247, 0xffff0000, v177
	v_fma_f32 v74, v74, 0.5, v246
	v_fma_f32 v75, v75, 0.5, v247
	v_fmac_f32_e32 v92, v74, v74
	v_fmac_f32_e32 v92, v75, v75
	v_cvt_pk_bf16_f32 v177, v74, v75
	ds_bpermute_b32 v250, v252, v238
	ds_bpermute_b32 v251, v252, v239
	ds_bpermute_b32 v174, v252, v174
	ds_bpermute_b32 v175, v252, v175
	ds_bpermute_b32 v176, v252, v176
	ds_bpermute_b32 v177, v252, v177
	s_waitcnt lgkmcnt(0)
	global_store_dwordx4 v[250:251], v[174:177], off
	v_lshlrev_b32_e32 v246, 16, v178
	v_and_b32_e32 v247, 0xffff0000, v178
	v_fma_f32 v68, v68, 0.5, v246
	v_fma_f32 v69, v69, 0.5, v247
	v_fmac_f32_e32 v92, v68, v68
	v_fmac_f32_e32 v92, v69, v69
	v_cvt_pk_bf16_f32 v178, v68, v69
	v_lshlrev_b32_e32 v246, 16, v179
	v_and_b32_e32 v247, 0xffff0000, v179
	v_fma_f32 v70, v70, 0.5, v246
	v_fma_f32 v71, v71, 0.5, v247
	v_fmac_f32_e32 v92, v70, v70
	v_fmac_f32_e32 v92, v71, v71
	v_cvt_pk_bf16_f32 v179, v70, v71
	v_lshlrev_b32_e32 v246, 16, v180
	v_and_b32_e32 v247, 0xffff0000, v180
	v_fma_f32 v64, v64, 0.5, v246
	v_fma_f32 v65, v65, 0.5, v247
	v_fmac_f32_e32 v92, v64, v64
	v_fmac_f32_e32 v92, v65, v65
	v_cvt_pk_bf16_f32 v180, v64, v65
	v_lshlrev_b32_e32 v246, 16, v181
	v_and_b32_e32 v247, 0xffff0000, v181
	v_fma_f32 v66, v66, 0.5, v246
	v_fma_f32 v67, v67, 0.5, v247
	v_fmac_f32_e32 v92, v66, v66
	v_fmac_f32_e32 v92, v67, v67
	v_cvt_pk_bf16_f32 v181, v66, v67
	ds_bpermute_b32 v178, v252, v178
	ds_bpermute_b32 v179, v252, v179
	ds_bpermute_b32 v180, v252, v180
	ds_bpermute_b32 v181, v252, v181
	s_waitcnt lgkmcnt(0)
	global_store_dwordx4 v[250:251], v[178:181], off offset:256
	s_waitcnt vmcnt(14)
	s_mov_b32 s100, 0x80000
	v_lshl_add_u64 v[238:239], v[236:237], 0, s[100:101]
	v_lshlrev_b32_e32 v246, 16, v184
	v_and_b32_e32 v247, 0xffff0000, v184
	v_fma_f32 v60, v60, 0.5, v246
	v_fma_f32 v61, v61, 0.5, v247
	v_mul_f32_e32 v76, v60, v60
	v_fmac_f32_e32 v76, v61, v61
	v_cvt_pk_bf16_f32 v184, v60, v61
	v_lshlrev_b32_e32 v246, 16, v185
	v_and_b32_e32 v247, 0xffff0000, v185
	v_fma_f32 v62, v62, 0.5, v246
	v_fma_f32 v63, v63, 0.5, v247
	v_fmac_f32_e32 v76, v62, v62
	v_fmac_f32_e32 v76, v63, v63
	v_cvt_pk_bf16_f32 v185, v62, v63
	v_lshlrev_b32_e32 v246, 16, v186
	v_and_b32_e32 v247, 0xffff0000, v186
	v_fma_f32 v56, v56, 0.5, v246
	v_fma_f32 v57, v57, 0.5, v247
	v_fmac_f32_e32 v76, v56, v56
	v_fmac_f32_e32 v76, v57, v57
	v_cvt_pk_bf16_f32 v186, v56, v57
	v_lshlrev_b32_e32 v246, 16, v187
	v_and_b32_e32 v247, 0xffff0000, v187
	v_fma_f32 v58, v58, 0.5, v246
	v_fma_f32 v59, v59, 0.5, v247
	v_fmac_f32_e32 v76, v58, v58
	v_fmac_f32_e32 v76, v59, v59
	v_cvt_pk_bf16_f32 v187, v58, v59
	ds_bpermute_b32 v250, v252, v238
	ds_bpermute_b32 v251, v252, v239
	ds_bpermute_b32 v184, v252, v184
	ds_bpermute_b32 v185, v252, v185
	ds_bpermute_b32 v186, v252, v186
	ds_bpermute_b32 v187, v252, v187
	s_waitcnt lgkmcnt(0)
	global_store_dwordx4 v[250:251], v[184:187], off
	v_lshlrev_b32_e32 v246, 16, v188
	v_and_b32_e32 v247, 0xffff0000, v188
	v_fma_f32 v52, v52, 0.5, v246
	v_fma_f32 v53, v53, 0.5, v247
	v_fmac_f32_e32 v76, v52, v52
	v_fmac_f32_e32 v76, v53, v53
	v_cvt_pk_bf16_f32 v188, v52, v53
	v_lshlrev_b32_e32 v246, 16, v189
	v_and_b32_e32 v247, 0xffff0000, v189
	v_fma_f32 v54, v54, 0.5, v246
	v_fma_f32 v55, v55, 0.5, v247
	v_fmac_f32_e32 v76, v54, v54
	v_fmac_f32_e32 v76, v55, v55
	v_cvt_pk_bf16_f32 v189, v54, v55
	v_lshlrev_b32_e32 v246, 16, v190
	v_and_b32_e32 v247, 0xffff0000, v190
	v_fma_f32 v48, v48, 0.5, v246
	v_fma_f32 v49, v49, 0.5, v247
	v_fmac_f32_e32 v76, v48, v48
	v_fmac_f32_e32 v76, v49, v49
	v_cvt_pk_bf16_f32 v190, v48, v49
	v_lshlrev_b32_e32 v246, 16, v191
	v_and_b32_e32 v247, 0xffff0000, v191
	v_fma_f32 v50, v50, 0.5, v246
	v_fma_f32 v51, v51, 0.5, v247
	v_fmac_f32_e32 v76, v50, v50
	v_fmac_f32_e32 v76, v51, v51
	v_cvt_pk_bf16_f32 v191, v50, v51
	ds_bpermute_b32 v188, v252, v188
	ds_bpermute_b32 v189, v252, v189
	ds_bpermute_b32 v190, v252, v190
	ds_bpermute_b32 v191, v252, v191
	s_waitcnt lgkmcnt(0)
	global_store_dwordx4 v[250:251], v[188:191], off offset:256
	s_waitcnt vmcnt(14)
	s_mov_b32 s100, 0x90000
	v_lshl_add_u64 v[238:239], v[236:237], 0, s[100:101]
	v_lshlrev_b32_e32 v246, 16, v192
	v_and_b32_e32 v247, 0xffff0000, v192
	v_fma_f32 v44, v44, 0.5, v246
	v_fma_f32 v45, v45, 0.5, v247
	v_mul_f32_e32 v60, v44, v44
	v_fmac_f32_e32 v60, v45, v45
	v_cvt_pk_bf16_f32 v192, v44, v45
	v_lshlrev_b32_e32 v246, 16, v193
	v_and_b32_e32 v247, 0xffff0000, v193
	v_fma_f32 v46, v46, 0.5, v246
	v_fma_f32 v47, v47, 0.5, v247
	v_fmac_f32_e32 v60, v46, v46
	v_fmac_f32_e32 v60, v47, v47
	v_cvt_pk_bf16_f32 v193, v46, v47
	v_lshlrev_b32_e32 v246, 16, v194
	v_and_b32_e32 v247, 0xffff0000, v194
	v_fma_f32 v40, v40, 0.5, v246
	v_fma_f32 v41, v41, 0.5, v247
	v_fmac_f32_e32 v60, v40, v40
	v_fmac_f32_e32 v60, v41, v41
	v_cvt_pk_bf16_f32 v194, v40, v41
	v_lshlrev_b32_e32 v246, 16, v195
	v_and_b32_e32 v247, 0xffff0000, v195
	v_fma_f32 v42, v42, 0.5, v246
	v_fma_f32 v43, v43, 0.5, v247
	v_fmac_f32_e32 v60, v42, v42
	v_fmac_f32_e32 v60, v43, v43
	v_cvt_pk_bf16_f32 v195, v42, v43
	ds_bpermute_b32 v250, v252, v238
	ds_bpermute_b32 v251, v252, v239
	ds_bpermute_b32 v192, v252, v192
	ds_bpermute_b32 v193, v252, v193
	ds_bpermute_b32 v194, v252, v194
	ds_bpermute_b32 v195, v252, v195
	s_waitcnt lgkmcnt(0)
	global_store_dwordx4 v[250:251], v[192:195], off
	v_lshlrev_b32_e32 v246, 16, v196
	v_and_b32_e32 v247, 0xffff0000, v196
	v_fma_f32 v36, v36, 0.5, v246
	v_fma_f32 v37, v37, 0.5, v247
	v_fmac_f32_e32 v60, v36, v36
	v_fmac_f32_e32 v60, v37, v37
	v_cvt_pk_bf16_f32 v196, v36, v37
	v_lshlrev_b32_e32 v246, 16, v197
	v_and_b32_e32 v247, 0xffff0000, v197
	v_fma_f32 v38, v38, 0.5, v246
	v_fma_f32 v39, v39, 0.5, v247
	v_fmac_f32_e32 v60, v38, v38
	v_fmac_f32_e32 v60, v39, v39
	v_cvt_pk_bf16_f32 v197, v38, v39
	v_lshlrev_b32_e32 v246, 16, v198
	v_and_b32_e32 v247, 0xffff0000, v198
	v_fma_f32 v32, v32, 0.5, v246
	v_fma_f32 v33, v33, 0.5, v247
	v_fmac_f32_e32 v60, v32, v32
	v_fmac_f32_e32 v60, v33, v33
	v_cvt_pk_bf16_f32 v198, v32, v33
	v_lshlrev_b32_e32 v246, 16, v199
	v_and_b32_e32 v247, 0xffff0000, v199
	v_fma_f32 v34, v34, 0.5, v246
	v_fma_f32 v35, v35, 0.5, v247
	v_fmac_f32_e32 v60, v34, v34
	v_fmac_f32_e32 v60, v35, v35
	v_cvt_pk_bf16_f32 v199, v34, v35
	ds_bpermute_b32 v196, v252, v196
	ds_bpermute_b32 v197, v252, v197
	ds_bpermute_b32 v198, v252, v198
	ds_bpermute_b32 v199, v252, v199
	s_waitcnt lgkmcnt(0)
	global_store_dwordx4 v[250:251], v[196:199], off offset:256
	s_waitcnt vmcnt(14)
	s_mov_b32 s100, 0xa0000
	v_lshl_add_u64 v[238:239], v[236:237], 0, s[100:101]
	v_lshlrev_b32_e32 v246, 16, v200
	v_and_b32_e32 v247, 0xffff0000, v200
	v_fma_f32 v28, v28, 0.5, v246
	v_fma_f32 v29, v29, 0.5, v247
	v_mul_f32_e32 v44, v28, v28
	v_fmac_f32_e32 v44, v29, v29
	v_cvt_pk_bf16_f32 v200, v28, v29
	v_lshlrev_b32_e32 v246, 16, v201
	v_and_b32_e32 v247, 0xffff0000, v201
	v_fma_f32 v30, v30, 0.5, v246
	v_fma_f32 v31, v31, 0.5, v247
	v_fmac_f32_e32 v44, v30, v30
	v_fmac_f32_e32 v44, v31, v31
	v_cvt_pk_bf16_f32 v201, v30, v31
	v_lshlrev_b32_e32 v246, 16, v202
	v_and_b32_e32 v247, 0xffff0000, v202
	v_fma_f32 v24, v24, 0.5, v246
	v_fma_f32 v25, v25, 0.5, v247
	v_fmac_f32_e32 v44, v24, v24
	v_fmac_f32_e32 v44, v25, v25
	v_cvt_pk_bf16_f32 v202, v24, v25
	v_lshlrev_b32_e32 v246, 16, v203
	v_and_b32_e32 v247, 0xffff0000, v203
	v_fma_f32 v26, v26, 0.5, v246
	v_fma_f32 v27, v27, 0.5, v247
	v_fmac_f32_e32 v44, v26, v26
	v_fmac_f32_e32 v44, v27, v27
	v_cvt_pk_bf16_f32 v203, v26, v27
	ds_bpermute_b32 v250, v252, v238
	ds_bpermute_b32 v251, v252, v239
	ds_bpermute_b32 v200, v252, v200
	ds_bpermute_b32 v201, v252, v201
	ds_bpermute_b32 v202, v252, v202
	ds_bpermute_b32 v203, v252, v203
	s_waitcnt lgkmcnt(0)
	global_store_dwordx4 v[250:251], v[200:203], off
	v_lshlrev_b32_e32 v246, 16, v204
	v_and_b32_e32 v247, 0xffff0000, v204
	v_fma_f32 v20, v20, 0.5, v246
	v_fma_f32 v21, v21, 0.5, v247
	v_fmac_f32_e32 v44, v20, v20
	v_fmac_f32_e32 v44, v21, v21
	v_cvt_pk_bf16_f32 v204, v20, v21
	v_lshlrev_b32_e32 v246, 16, v205
	v_and_b32_e32 v247, 0xffff0000, v205
	v_fma_f32 v22, v22, 0.5, v246
	v_fma_f32 v23, v23, 0.5, v247
	v_fmac_f32_e32 v44, v22, v22
	v_fmac_f32_e32 v44, v23, v23
	v_cvt_pk_bf16_f32 v205, v22, v23
	v_lshlrev_b32_e32 v246, 16, v206
	v_and_b32_e32 v247, 0xffff0000, v206
	v_fma_f32 v16, v16, 0.5, v246
	v_fma_f32 v17, v17, 0.5, v247
	v_fmac_f32_e32 v44, v16, v16
	v_fmac_f32_e32 v44, v17, v17
	v_cvt_pk_bf16_f32 v206, v16, v17
	v_lshlrev_b32_e32 v246, 16, v207
	v_and_b32_e32 v247, 0xffff0000, v207
	v_fma_f32 v18, v18, 0.5, v246
	v_fma_f32 v19, v19, 0.5, v247
	v_fmac_f32_e32 v44, v18, v18
	v_fmac_f32_e32 v44, v19, v19
	v_cvt_pk_bf16_f32 v207, v18, v19
	ds_bpermute_b32 v204, v252, v204
	ds_bpermute_b32 v205, v252, v205
	ds_bpermute_b32 v206, v252, v206
	ds_bpermute_b32 v207, v252, v207
	s_waitcnt lgkmcnt(0)
	global_store_dwordx4 v[250:251], v[204:207], off offset:256
	s_waitcnt vmcnt(14)
	s_mov_b32 s100, 0xb0000
	v_lshl_add_u64 v[238:239], v[236:237], 0, s[100:101]
	v_lshlrev_b32_e32 v246, 16, v208
	v_and_b32_e32 v247, 0xffff0000, v208
	v_fma_f32 v12, v12, 0.5, v246
	v_fma_f32 v13, v13, 0.5, v247
	v_mul_f32_e32 v28, v12, v12
	v_fmac_f32_e32 v28, v13, v13
	v_cvt_pk_bf16_f32 v208, v12, v13
	v_lshlrev_b32_e32 v246, 16, v209
	v_and_b32_e32 v247, 0xffff0000, v209
	v_fma_f32 v14, v14, 0.5, v246
	v_fma_f32 v15, v15, 0.5, v247
	v_fmac_f32_e32 v28, v14, v14
	v_fmac_f32_e32 v28, v15, v15
	v_cvt_pk_bf16_f32 v209, v14, v15
	v_lshlrev_b32_e32 v246, 16, v210
	v_and_b32_e32 v247, 0xffff0000, v210
	v_fma_f32 v8, v8, 0.5, v246
	v_fma_f32 v9, v9, 0.5, v247
	v_fmac_f32_e32 v28, v8, v8
	v_fmac_f32_e32 v28, v9, v9
	v_cvt_pk_bf16_f32 v210, v8, v9
	v_lshlrev_b32_e32 v246, 16, v211
	v_and_b32_e32 v247, 0xffff0000, v211
	v_fma_f32 v10, v10, 0.5, v246
	v_fma_f32 v11, v11, 0.5, v247
	v_fmac_f32_e32 v28, v10, v10
	v_fmac_f32_e32 v28, v11, v11
	v_cvt_pk_bf16_f32 v211, v10, v11
	ds_bpermute_b32 v250, v252, v238
	ds_bpermute_b32 v251, v252, v239
	ds_bpermute_b32 v208, v252, v208
	ds_bpermute_b32 v209, v252, v209
	ds_bpermute_b32 v210, v252, v210
	ds_bpermute_b32 v211, v252, v211
	s_waitcnt lgkmcnt(0)
	global_store_dwordx4 v[250:251], v[208:211], off
	v_lshlrev_b32_e32 v246, 16, v212
	v_and_b32_e32 v247, 0xffff0000, v212
	v_fma_f32 v4, v4, 0.5, v246
	v_fma_f32 v5, v5, 0.5, v247
	v_fmac_f32_e32 v28, v4, v4
	v_fmac_f32_e32 v28, v5, v5
	v_cvt_pk_bf16_f32 v212, v4, v5
	v_lshlrev_b32_e32 v246, 16, v213
	v_and_b32_e32 v247, 0xffff0000, v213
	v_fma_f32 v6, v6, 0.5, v246
	v_fma_f32 v7, v7, 0.5, v247
	v_fmac_f32_e32 v28, v6, v6
	v_fmac_f32_e32 v28, v7, v7
	v_cvt_pk_bf16_f32 v213, v6, v7
	v_lshlrev_b32_e32 v246, 16, v214
	v_and_b32_e32 v247, 0xffff0000, v214
	v_fma_f32 v0, v0, 0.5, v246
	v_fma_f32 v1, v1, 0.5, v247
	v_fmac_f32_e32 v28, v0, v0
	v_fmac_f32_e32 v28, v1, v1
	v_cvt_pk_bf16_f32 v214, v0, v1
	v_lshlrev_b32_e32 v246, 16, v215
	v_and_b32_e32 v247, 0xffff0000, v215
	v_fma_f32 v2, v2, 0.5, v246
	v_fma_f32 v3, v3, 0.5, v247
	v_fmac_f32_e32 v28, v2, v2
	v_fmac_f32_e32 v28, v3, v3
	v_cvt_pk_bf16_f32 v215, v2, v3
	ds_bpermute_b32 v212, v252, v212
	ds_bpermute_b32 v213, v252, v213
	ds_bpermute_b32 v214, v252, v214
	ds_bpermute_b32 v215, v252, v215
	s_waitcnt lgkmcnt(0)
	global_store_dwordx4 v[250:251], v[212:215], off offset:256
	ds_bpermute_b32 v0, v244, v248
	ds_bpermute_b32 v1, v244, v124
	ds_bpermute_b32 v2, v244, v108
	ds_bpermute_b32 v3, v244, v92
	ds_bpermute_b32 v8, v244, v76
	ds_bpermute_b32 v9, v244, v60
	ds_bpermute_b32 v10, v244, v44
	ds_bpermute_b32 v11, v244, v28
	s_waitcnt lgkmcnt(7)
	v_add_f32_e32 v248, v248, v0
	s_waitcnt lgkmcnt(6)
	v_add_f32_e32 v124, v124, v1
	s_waitcnt lgkmcnt(5)
	v_add_f32_e32 v108, v108, v2
	s_waitcnt lgkmcnt(4)
	v_add_f32_e32 v92, v92, v3
	s_waitcnt lgkmcnt(3)
	v_add_f32_e32 v76, v76, v8
	s_waitcnt lgkmcnt(2)
	v_add_f32_e32 v60, v60, v9
	s_waitcnt lgkmcnt(1)
	v_add_f32_e32 v44, v44, v10
	s_waitcnt lgkmcnt(0)
	v_add_f32_e32 v28, v28, v11
	ds_bpermute_b32 v0, v245, v248
	ds_bpermute_b32 v1, v245, v124
	ds_bpermute_b32 v2, v245, v108
	ds_bpermute_b32 v3, v245, v92
	ds_bpermute_b32 v8, v245, v76
	ds_bpermute_b32 v9, v245, v60
	ds_bpermute_b32 v10, v245, v44
	ds_bpermute_b32 v11, v245, v28
	s_waitcnt lgkmcnt(7)
	v_add_f32_e32 v248, v248, v0
	s_waitcnt lgkmcnt(6)
	v_add_f32_e32 v124, v124, v1
	s_waitcnt lgkmcnt(5)
	v_add_f32_e32 v108, v108, v2
	s_waitcnt lgkmcnt(4)
	v_add_f32_e32 v92, v92, v3
	s_waitcnt lgkmcnt(3)
	v_add_f32_e32 v76, v76, v8
	s_waitcnt lgkmcnt(2)
	v_add_f32_e32 v60, v60, v9
	s_waitcnt lgkmcnt(1)
	v_add_f32_e32 v44, v44, v10
	s_waitcnt lgkmcnt(0)
	v_add_f32_e32 v28, v28, v11
	s_and_saveexec_b64 s[18:19], s[8:9]
	v_lshl_add_u64 v[236:237], v[240:241], 3, s[10:11]
	v_mul_f32_e32 v248, 0x4f800000, v248
	v_trunc_f32_e32 v248, v248
	v_mul_f32_e32 v0, 0x2f800000, v248
	v_floor_f32_e32 v0, v0
	v_fmac_f32_e32 v248, 0xcf800000, v0
	v_cvt_u32_f32_e32 v246, v248
	v_cvt_u32_f32_e32 v247, v0
	global_atomic_add_x2 v[236:237], v[246:247], off
	s_nop 1
	v_mul_f32_e32 v124, 0x4f800000, v124
	v_trunc_f32_e32 v124, v124
	v_mul_f32_e32 v1, 0x2f800000, v124
	v_floor_f32_e32 v1, v1
	v_fmac_f32_e32 v124, 0xcf800000, v1
	v_cvt_u32_f32_e32 v246, v124
	v_cvt_u32_f32_e32 v247, v1
	global_atomic_add_x2 v[236:237], v[246:247], off offset:128
	s_nop 1
	v_mul_f32_e32 v108, 0x4f800000, v108
	v_trunc_f32_e32 v108, v108
	v_mul_f32_e32 v2, 0x2f800000, v108
	v_floor_f32_e32 v2, v2
	v_fmac_f32_e32 v108, 0xcf800000, v2
	v_cvt_u32_f32_e32 v246, v108
	v_cvt_u32_f32_e32 v247, v2
	global_atomic_add_x2 v[236:237], v[246:247], off offset:256
	s_nop 1
	v_mul_f32_e32 v92, 0x4f800000, v92
	v_trunc_f32_e32 v92, v92
	v_mul_f32_e32 v3, 0x2f800000, v92
	v_floor_f32_e32 v3, v3
	v_fmac_f32_e32 v92, 0xcf800000, v3
	v_cvt_u32_f32_e32 v246, v92
	v_cvt_u32_f32_e32 v247, v3
	global_atomic_add_x2 v[236:237], v[246:247], off offset:384
	s_nop 1
	v_mul_f32_e32 v76, 0x4f800000, v76
	v_trunc_f32_e32 v76, v76
	v_mul_f32_e32 v8, 0x2f800000, v76
	v_floor_f32_e32 v8, v8
	v_fmac_f32_e32 v76, 0xcf800000, v8
	v_cvt_u32_f32_e32 v246, v76
	v_cvt_u32_f32_e32 v247, v8
	global_atomic_add_x2 v[236:237], v[246:247], off offset:1024
	s_nop 1
	v_mul_f32_e32 v60, 0x4f800000, v60
	v_trunc_f32_e32 v60, v60
	v_mul_f32_e32 v9, 0x2f800000, v60
	v_floor_f32_e32 v9, v9
	v_fmac_f32_e32 v60, 0xcf800000, v9
	v_cvt_u32_f32_e32 v246, v60
	v_cvt_u32_f32_e32 v247, v9
	global_atomic_add_x2 v[236:237], v[246:247], off offset:1152
	s_nop 1
	v_mul_f32_e32 v44, 0x4f800000, v44
	v_trunc_f32_e32 v44, v44
	v_mul_f32_e32 v10, 0x2f800000, v44
	v_floor_f32_e32 v10, v10
	v_fmac_f32_e32 v44, 0xcf800000, v10
	v_cvt_u32_f32_e32 v246, v44
	v_cvt_u32_f32_e32 v247, v10
	global_atomic_add_x2 v[236:237], v[246:247], off offset:1280
	s_nop 1
	v_mul_f32_e32 v28, 0x4f800000, v28
	v_trunc_f32_e32 v28, v28
	v_mul_f32_e32 v11, 0x2f800000, v28
	v_floor_f32_e32 v11, v11
	v_fmac_f32_e32 v28, 0xcf800000, v11
	v_cvt_u32_f32_e32 v246, v28
	v_cvt_u32_f32_e32 v247, v11
	global_atomic_add_x2 v[236:237], v[246:247], off offset:1408
	s_nop 1
